# sg_branch cross-segment operand prefetch, attn_sample score-stage reads batched + single reciprocal/broadcast batch, ret_out a2 fragment reads batched, conv loop packed f32
# speedup vs baseline: 1.0127x; 1.0127x over previous
; DEV float log_gamma(int h) { return log1pf(-exp2f(-5.0f - (float)h)); }
; DEV void ret_out_item(const Params& p, int l, int item, unsigned char* smem) {
;     ...
;   const float lg = log_gamma(h);
;   {
;     u32x4 q[2], k[2], v[4], g[4];
; #pragma unroll
;     for (int i = 0; i < 2; ++i) {
;       const int c = tid + i * 512, r = c >> 3, kc = c & 7;
;       q[i] = *(const u32x4*)(Z + (rowbase + r) * NIN + RQ + h * 64 + kc * 8);
;       k[i] = *(const u32x4*)(Z + (rowbase + r) * NIN + RK + h * 64 + kc * 8);
;     }
.LBB0_85:
	s_ashr_i32 s0, s18, 7
	s_ashr_i32 s1, s0, 31
	s_bfe_u32 s4, s18, 0x20005
	s_lshl_b64 s[38:39], s[0:1], 12
	s_lshl_b32 s0, s18, 7
	s_and_b32 s0, s0, 0xf80
	v_cvt_f32_ubyte0_e32 v0, s4
	s_or_b32 s38, s38, s0
	v_sub_f32_e32 v0, 0xc0a00000, v0
	s_mov_b32 s0, 0xc2fc0000
	v_cmp_gt_f32_e32 vcc, s0, v0
	s_ashr_i32 s19, s18, 31
	s_lshl_b64 s[2:3], s[18:19], 14
	s_waitcnt lgkmcnt(0)
	v_cndmask_b32_e32 v1, 0, v203, vcc
	v_add_f32_e32 v0, v0, v1
	v_exp_f32_e32 v0, v0
	s_and_b64 s[0:1], vcc, exec
	s_cselect_b32 s0, 0xffffffc0, 0
	v_mov_b32_e32 v44, v171
	v_ldexp_f32 v33, v0, s0
	v_sub_f32_e32 v2, 1.0, v33
	v_add_f32_e32 v0, -1.0, v2
	v_sub_f32_e32 v1, v0, v2
	v_add_f32_e32 v1, 1.0, v1
	v_sub_f32_e64 v0, -v33, v0
	v_add_f32_e32 v3, v0, v1
	v_frexp_mant_f32_e32 v0, v2
	s_mov_b32 s0, 0x3f2aaaab
	v_cmp_gt_f32_e32 vcc, s0, v0
	v_cvt_f64_f32_e32 v[0:1], v2
	v_frexp_exp_i32_f64_e32 v0, v[0:1]
	v_subbrev_co_u32_e32 v0, vcc, 0, v0, vcc
	v_sub_u32_e32 v1, 0, v0
	v_ldexp_f32 v2, v2, v1
	v_ldexp_f32 v1, v3, v1
	v_add_f32_e32 v3, -1.0, v2
	v_add_f32_e32 v4, 1.0, v3
	v_sub_f32_e32 v4, v2, v4
	v_add_f32_e32 v4, v1, v4
	v_add_f32_e32 v5, v3, v4
	v_sub_f32_e32 v3, v5, v3
	v_sub_f32_e32 v3, v4, v3
	v_add_f32_e32 v4, 1.0, v2
	v_add_f32_e32 v6, -1.0, v4
	v_sub_f32_e32 v2, v2, v6
	v_add_f32_e32 v1, v1, v2
	v_add_f32_e32 v2, v4, v1
	v_sub_f32_e32 v4, v2, v4
	v_sub_f32_e32 v1, v1, v4
	v_rcp_f32_e32 v4, v2
	v_cvt_f32_i32_e32 v0, v0
	s_mov_b32 s0, 0x3f317218
	v_mul_f32_e32 v6, v5, v4
	v_mul_f32_e32 v7, v2, v6
	v_fma_f32 v8, v6, v2, -v7
	v_fmac_f32_e32 v8, v6, v1
	v_add_f32_e32 v9, v7, v8
	v_sub_f32_e32 v10, v5, v9
	v_sub_f32_e32 v5, v5, v10
	v_sub_f32_e32 v7, v9, v7
	v_sub_f32_e32 v5, v5, v9
	v_add_f32_e32 v3, v3, v5
	v_sub_f32_e32 v5, v7, v8
	v_add_f32_e32 v3, v5, v3
	v_add_f32_e32 v5, v10, v3
	v_mul_f32_e32 v7, v4, v5
	v_mul_f32_e32 v8, v2, v7
	v_fma_f32 v2, v7, v2, -v8
	v_fmac_f32_e32 v2, v7, v1
	v_sub_f32_e32 v1, v10, v5
	v_add_f32_e32 v1, v3, v1
	v_add_f32_e32 v3, v8, v2
	v_sub_f32_e32 v9, v5, v3
	v_sub_f32_e32 v5, v5, v9
	v_sub_f32_e32 v8, v3, v8
	v_sub_f32_e32 v3, v5, v3
	v_add_f32_e32 v1, v1, v3
	v_sub_f32_e32 v2, v8, v2
	v_add_f32_e32 v1, v2, v1
	v_add_f32_e32 v2, v6, v7
	v_add_f32_e32 v1, v9, v1
	v_sub_f32_e32 v3, v2, v6
	v_mul_f32_e32 v1, v4, v1
	v_sub_f32_e32 v3, v7, v3
	v_add_f32_e32 v1, v3, v1
	v_mul_f32_e32 v6, 0x3f317218, v0
	v_add_f32_e32 v3, v2, v1
	v_fma_f32 v7, v0, s0, -v6
	v_mul_f32_e32 v4, v3, v3
	v_fmac_f32_e32 v7, 0xb102e308, v0
	v_sub_f32_e32 v0, v3, v2
	v_fmamk_f32 v5, v4, 0x3e9b6dac, v201
	v_sub_f32_e32 v0, v1, v0
	v_add_f32_e32 v1, v6, v7
	v_fmaak_f32 v5, v4, v5, 0x3f2aaada
	v_sub_f32_e32 v2, v1, v6
	v_ldexp_f32 v6, v3, 1
	v_mul_f32_e32 v3, v3, v4
	v_mul_f32_e32 v3, v3, v5
	v_add_f32_e32 v4, v6, v3
	v_sub_f32_e32 v5, v4, v6
	v_ldexp_f32 v0, v0, 1
	v_sub_f32_e32 v3, v3, v5
	v_add_f32_e32 v0, v0, v3
	v_add_f32_e32 v3, v4, v0
	v_sub_f32_e32 v4, v3, v4
	v_sub_f32_e32 v0, v0, v4
	v_add_f32_e32 v4, v1, v3
	v_sub_f32_e32 v5, v4, v1
	v_sub_f32_e32 v6, v4, v5
	v_sub_f32_e32 v2, v7, v2
	v_sub_f32_e32 v1, v1, v6
	v_sub_f32_e32 v3, v3, v5
	v_add_f32_e32 v1, v3, v1
	v_add_f32_e32 v3, v2, v0
	v_sub_f32_e32 v5, v3, v2
	v_sub_f32_e32 v6, v3, v5
	v_add_f32_e32 v1, v3, v1
	v_sub_f32_e32 v2, v2, v6
	v_sub_f32_e32 v0, v0, v5
	v_add_f32_e32 v5, v4, v1
	v_add_f32_e32 v0, v0, v2
	v_sub_f32_e32 v2, v5, v4
	v_ashrrev_i32_e32 v16, 3, v44
	v_sub_f32_e32 v1, v1, v2
	v_ashrrev_i32_e32 v17, 31, v16
	v_add_f32_e32 v4, v0, v1
	s_mov_b32 s0, 0x33800000
	v_lshl_add_u64 v[0:1], s[38:39], 0, v[16:17]
	v_mov_b64_e32 v[12:13], s[30:31]
	v_cmp_gt_f32_e32 vcc, s0, v33
	v_mad_u64_u32 v[2:3], s[0:1], v0, s95, v[12:13]
	v_mad_i32_i24 v3, v1, s95, v3
	s_lshl_b32 s6, s4, 7
	v_lshl_add_u64 v[0:1], v[2:3], 0, s[6:7]
	v_lshlrev_b32_e32 v2, 4, v44
	v_add_u32_e32 v7, 0x200, v44
	v_and_b32_e32 v168, 0x70, v2
	v_ashrrev_i32_e32 v18, 3, v7
	v_lshl_add_u64 v[0:1], v[0:1], 0, v[168:169]
	v_ashrrev_i32_e32 v19, 31, v18
	global_load_dwordx4 v[48:51], v[0:1], off
	global_load_dwordx4 v[52:55], v[0:1], off offset:512
	v_lshl_add_u64 v[0:1], s[38:39], 0, v[18:19]
	v_mad_u64_u32 v[2:3], s[0:1], v0, s95, v[12:13]
	v_mad_i32_i24 v3, v1, s95, v3
	v_lshl_add_u64 v[0:1], v[2:3], 0, s[6:7]
	v_lshl_add_u64 v[0:1], v[0:1], 0, v[168:169]
	global_load_dwordx4 v[56:59], v[0:1], off
	global_load_dwordx4 v[60:63], v[0:1], off offset:512
	v_add_f32_e32 v0, v5, v4
	v_cmp_nlt_f32_e64 s[0:1], 1.0, v33
	v_and_b32_e32 v32, 0x7f, v44
	v_add_u32_e32 v8, 0x400, v44
	v_cndmask_b32_e64 v0, v204, v0, s[0:1]
	v_cmp_neq_f32_e64 s[0:1], 1.0, v33
	v_add_u32_e32 v17, 0x600, v44
	v_ashrrev_i32_e32 v40, 4, v44
	v_cndmask_b32_e64 v46, v205, v0, s[0:1]
	v_or_b32_e32 v0, s38, v32
	v_mad_u64_u32 v[0:1], s[0:1], v0, s95, v[12:13]
	v_ashrrev_i32_e32 v20, 4, v7
	v_ashrrev_i32_e32 v22, 4, v8
	v_ashrrev_i32_e32 v24, 4, v17
	v_lshlrev_b32_e32 v6, 3, v44
	v_mad_i32_i24 v1, s39, v206, v1
	s_lshl_b32 s0, s4, 8
	s_mov_b32 s1, s7
	v_and_b32_e32 v64, -8, v40
	v_and_b32_e32 v26, -8, v20
	v_and_b32_e32 v28, -8, v22
	v_and_b32_e32 v30, -8, v24
	v_lshl_add_u64 v[14:15], v[0:1], 0, s[0:1]
	v_and_b32_e32 v4, 0x78, v6
	v_ashrrev_i32_e32 v65, 31, v64
	v_ashrrev_i32_e32 v41, 31, v40
	v_ashrrev_i32_e32 v27, 31, v26
	v_ashrrev_i32_e32 v21, 31, v20
	v_ashrrev_i32_e32 v29, 31, v28
	v_ashrrev_i32_e32 v23, 31, v22
	v_ashrrev_i32_e32 v31, 31, v30
	v_ashrrev_i32_e32 v25, 31, v24
	v_lshl_add_u64 v[42:43], v[64:65], 1, v[14:15]
	v_lshl_add_u64 v[0:1], s[38:39], 0, v[40:41]
	v_lshlrev_b32_e32 v76, 1, v4
	v_lshl_add_u64 v[38:39], v[26:27], 1, v[14:15]
	v_lshl_add_u64 v[4:5], s[38:39], 0, v[20:21]
	v_lshl_add_u64 v[36:37], v[28:29], 1, v[14:15]
; DEV void ret_out_item(const Params& p, int l, int item, unsigned char* smem) {
;     ...
;     u32x4 q[2], k[2], v[4], g[4];
; #pragma unroll
;     for (int i = 0; i < 2; ++i) {
;       const int c = tid + i * 512, r = c >> 3, kc = c & 7;
;       q[i] = *(const u32x4*)(Z + (rowbase + r) * NIN + RQ + h * 64 + kc * 8);
;       k[i] = *(const u32x4*)(Z + (rowbase + r) * NIN + RK + h * 64 + kc * 8);
;     }
; #pragma unroll
;     for (int i = 0; i < 4; ++i) {
;       const int c = tid + i * 512;
;       v[i] = *(const u32x4*)(Z + (rowbase + (c & 127)) * NIN + RV + h * 128 + (c >> 7) * 8);
;       g[i] = *(const u32x4*)(Z + (rowbase + (c >> 4)) * NIN + RG + h * 128 + (c & 15) * 8);
;     }
; #pragma unroll
;     for (int i = 0; i < 2; ++i) {
;       const int c = tid + i * 512, r = c >> 3, kc = c & 7;
;       *(u32x4*)(Qs + r * 144 + kc * 16) = q[i];
;       *(u32x4*)(Ks + r * 144 + kc * 16) = k[i];
;     }
; #pragma unroll
;     for (int i = 0; i < 4; ++i) {
;       const int c = tid + i * 512, r = c & 127, kc = c >> 7;
;       bf16_t* dst = Vt + (kc * 8) * 136 + r;
;       dst[0 * 136] = (bf16_t)(v[i].x & 0xffff); dst[1 * 136] = (bf16_t)(v[i].x >> 16);
;       dst[2 * 136] = (bf16_t)(v[i].y & 0xffff); dst[3 * 136] = (bf16_t)(v[i].y >> 16);
;       dst[4 * 136] = (bf16_t)(v[i].z & 0xffff); dst[5 * 136] = (bf16_t)(v[i].z >> 16);
;       dst[6 * 136] = (bf16_t)(v[i].w & 0xffff); dst[7 * 136] = (bf16_t)(v[i].w >> 16);
;       *(u32x4*)(Gs + (c >> 4) * 136 + (c & 15) * 8) = g[i];
;     }
; #pragma unroll
;     for (int i = 0; i < 2; ++i) {
;       const int c = tid + i * 512, r = c >> 3, kc = c & 7;
;       *(u32x4*)(smem + 106496 + r * 144 + kc * 16) = *(const u32x4*)(Sb + r * 64 + kc * 8);
;     }
;   }
;   __syncthreads();
	v_lshl_add_u64 v[8:9], s[38:39], 0, v[22:23]
	v_lshl_add_u64 v[34:35], v[30:31], 1, v[14:15]
	v_lshl_add_u64 v[14:15], s[38:39], 0, v[24:25]
	v_mad_u64_u32 v[2:3], s[4:5], v0, s95, v[12:13]
	v_mad_u64_u32 v[6:7], s[4:5], v4, s95, v[12:13]
	v_mad_u64_u32 v[10:11], s[4:5], v8, s95, v[12:13]
	v_mad_u64_u32 v[12:13], s[4:5], v14, s95, v[12:13]
	v_mad_i32_i24 v3, v1, s95, v3
	v_mad_i32_i24 v7, v5, s95, v7
	v_mad_i32_i24 v11, v9, s95, v11
	v_mad_i32_i24 v13, v15, s95, v13
	v_lshl_add_u64 v[0:1], v[2:3], 0, s[0:1]
	v_mov_b32_e32 v77, v169
	v_lshl_add_u64 v[4:5], v[6:7], 0, s[0:1]
	v_lshl_add_u64 v[8:9], v[10:11], 0, s[0:1]
	v_lshl_add_u64 v[12:13], v[12:13], 0, s[0:1]
	v_add_u32_e32 v21, 0, v168
	v_mul_lo_u32 v19, v16, s33
	v_lshl_add_u64 v[0:1], v[0:1], 0, v[76:77]
	v_lshl_add_u64 v[4:5], v[4:5], 0, v[76:77]
	v_lshl_add_u64 v[8:9], v[8:9], 0, v[76:77]
	v_lshl_add_u64 v[12:13], v[12:13], 0, v[76:77]
	v_add_u32_e32 v17, v21, v19
	global_load_dwordx4 v[0:3], v[0:1], off offset:2048
	s_add_u32 s0, s8, s2
	global_load_dwordx4 v[4:7], v[4:5], off offset:2048
	v_lshl_add_u32 v32, v32, 1, 0
	global_load_dwordx4 v[8:11], v[8:9], off offset:2048
	s_addc_u32 s1, s9, s3
	global_load_dwordx4 v[12:15], v[12:13], off offset:2048
	global_load_dwordx4 v[96:99], v[42:43], off offset:1024
	global_load_dwordx4 v[100:103], v[38:39], off offset:1024
	global_load_dwordx4 v[104:107], v[36:37], off offset:1024
	global_load_dwordx4 v[108:111], v[34:35], off offset:1024
	v_lshlrev_b32_e32 v112, 6, v16
	v_lshl_add_u64 v[114:115], s[0:1], 0, v[168:169]
	v_ashrrev_i32_e32 v113, 31, v112
	v_lshlrev_b32_e32 v120, 6, v18
	v_lshl_add_u64 v[112:113], v[112:113], 1, v[114:115]
	v_ashrrev_i32_e32 v121, 31, v120
	global_load_dwordx4 v[116:119], v[112:113], off
	v_lshl_add_u64 v[120:121], v[120:121], 1, v[114:115]
	global_load_dwordx4 v[124:127], v[120:121], off
	s_waitcnt vmcnt(13)
	ds_write_b128 v17, v[48:51]
	s_waitcnt vmcnt(12)
	ds_write_b128 v17, v[52:55] offset:18432
	v_mul_lo_u32 v17, v18, s33
	v_add_u32_e32 v21, v21, v17
	s_waitcnt vmcnt(11)
	ds_write_b128 v21, v[56:59]
	s_waitcnt vmcnt(10)
	ds_write_b128 v21, v[60:63] offset:18432
	v_mad_u64_u32 v[52:53], s[2:3], v64, s13, v[32:33]
	v_bfe_u32 v79, v44, 4, 2
	v_add_u32_e32 v78, s12, v76
	v_mad_u64_u32 v[42:43], s[2:3], v40, s13, v[78:79]
	v_ashrrev_i32_e32 v45, 6, v44
	v_and_b32_e32 v81, 15, v44
	v_lshlrev_b32_e32 v80, 4, v45
	v_or_b32_e32 v82, v80, v81
	s_movk_i32 s4, 0x110
	v_cndmask_b32_e64 v90, v46, -v33, vcc
	v_cmp_lt_i32_e32 vcc, -1, v45
	v_lshlrev_b32_e32 v83, 2, v79
	s_waitcnt vmcnt(5)
	ds_write_b16 v52, v96 offset:36864
	ds_write_b16_d16_hi v52, v96 offset:37136
	ds_write_b16 v52, v97 offset:37408
	ds_write_b16_d16_hi v52, v97 offset:37680
	ds_write_b16 v52, v98 offset:37952
	ds_write_b16_d16_hi v52, v98 offset:38224
	ds_write_b16 v52, v99 offset:38496
	ds_write_b16_d16_hi v52, v99 offset:38768
	ds_write_b128 v42, v[0:3]
	v_mad_u64_u32 v[0:1], s[2:3], v26, s13, v[32:33]
	s_waitcnt vmcnt(4)
	ds_write_b16 v0, v100 offset:36864
	ds_write_b16_d16_hi v0, v100 offset:37136
	ds_write_b16 v0, v101 offset:37408
	ds_write_b16_d16_hi v0, v101 offset:37680
	ds_write_b16 v0, v102 offset:37952
	ds_write_b16_d16_hi v0, v102 offset:38224
	ds_write_b16 v0, v103 offset:38496
	ds_write_b16_d16_hi v0, v103 offset:38768
	v_mad_u64_u32 v[0:1], s[2:3], v20, s13, v[78:79]
	ds_write_b128 v0, v[4:7]
	v_mad_u64_u32 v[0:1], s[2:3], v28, s13, v[32:33]
	s_waitcnt vmcnt(3)
	ds_write_b16 v0, v104 offset:36864
	ds_write_b16_d16_hi v0, v104 offset:37136
	ds_write_b16 v0, v105 offset:37408
	ds_write_b16_d16_hi v0, v105 offset:37680
	ds_write_b16 v0, v106 offset:37952
	ds_write_b16_d16_hi v0, v106 offset:38224
	ds_write_b16 v0, v107 offset:38496
	ds_write_b16_d16_hi v0, v107 offset:38768
	v_mad_u64_u32 v[0:1], s[2:3], v22, s13, v[78:79]
	ds_write_b128 v0, v[8:11]
	v_mad_u64_u32 v[0:1], s[2:3], v30, s13, v[32:33]
	s_waitcnt vmcnt(2)
	ds_write_b16 v0, v108 offset:36864
	ds_write_b16_d16_hi v0, v108 offset:37136
	ds_write_b16 v0, v109 offset:37408
	ds_write_b16_d16_hi v0, v109 offset:37680
	ds_write_b16 v0, v110 offset:37952
	ds_write_b16_d16_hi v0, v110 offset:38224
	ds_write_b16 v0, v111 offset:38496
	ds_write_b16_d16_hi v0, v111 offset:38768
	v_mad_u64_u32 v[0:1], s[2:3], v24, s13, v[78:79]
	ds_write_b128 v0, v[12:15]
	v_readlane_b32 s0, v248, 16
	v_and_b32_e32 v32, 48, v44
	v_mul_u32_u24_e32 v34, 0x90, v81
	v_add_u32_e32 v6, s0, v168
	v_add_u32_e32 v7, v6, v19
	v_add3_u32 v35, s0, v32, v34
	s_waitcnt vmcnt(1)
	ds_write_b128 v7, v[116:119]
	v_add_u32_e32 v4, v6, v17
	s_waitcnt vmcnt(0)
	ds_write_b128 v4, v[124:127]
	v_mul_lo_u32 v0, v82, s33
	v_add3_u32 v0, 0, v0, v32
	s_waitcnt lgkmcnt(0)
	s_barrier
; DEV f32x4 mfma32(bf16x8 a, bf16x8 b, f32x4 c) { return __builtin_amdgcn_mfma_f32_16x16x32_bf16(a, b, c, 0, 0, 0); }
; DEV void ret_out_item(const Params& p, int l, int item, unsigned char* smem) {
;     ...
;   bf16x8 qf[2];
; #pragma unroll
;   for (int ks = 0; ks < 2; ++ks) qf[ks] = *(const bf16x8*)(Qs + (w * 16 + fr) * 144 + ks * 64 + fq * 16);
;   f32x4 a1[8], a2[8];
; #pragma unroll
;   for (int et = 0; et < 8; ++et) {
;     a1[et] = (f32x4){0.f, 0.f, 0.f, 0.f};
;     a2[et] = (f32x4){0.f, 0.f, 0.f, 0.f};
; #pragma unroll
;     for (int ks = 0; ks < 2; ++ks) {
;       const bf16x8 sf = *(const bf16x8*)(smem + 106496 + (et * 16 + fr) * 144 + ks * 64 + fq * 16);
;       a2[et] = mfma32(qf[ks], sf, a2[et]);
;     }
;   }
;   const int qi = w * 16 + fr;
;   for (int jt = 0; jt <= w; ++jt) {
	ds_read_b128 v[64:67], v0
	ds_read_b128 v[68:71], v0 offset:64
	ds_read_b128 v[0:3], v35
	ds_read_b128 v[128:131], v35 offset:64
	ds_read_b128 v[4:7], v35 offset:2304
	ds_read_b128 v[132:135], v35 offset:2368
	ds_read_b128 v[8:11], v35 offset:4608
	ds_read_b128 v[136:139], v35 offset:4672
	ds_read_b128 v[12:15], v35 offset:6912
	ds_read_b128 v[140:143], v35 offset:6976
	ds_read_b128 v[16:19], v35 offset:9216
	ds_read_b128 v[144:147], v35 offset:9280
	ds_read_b128 v[20:23], v35 offset:11520
	ds_read_b128 v[148:151], v35 offset:11584
	ds_read_b128 v[24:27], v35 offset:13824
	ds_read_b128 v[152:155], v35 offset:13888
	ds_read_b128 v[28:31], v35 offset:16128
	ds_read_b128 v[156:159], v35 offset:16192
	s_waitcnt lgkmcnt(14)
	v_mfma_f32_16x16x32_bf16 v[0:3], v[64:67], v[0:3], 0
	v_mfma_f32_16x16x32_bf16 v[0:3], v[68:71], v[128:131], v[0:3]
	s_waitcnt lgkmcnt(12)
	v_mfma_f32_16x16x32_bf16 v[4:7], v[64:67], v[4:7], 0
	v_mfma_f32_16x16x32_bf16 v[4:7], v[68:71], v[132:135], v[4:7]
	s_waitcnt lgkmcnt(10)
	v_mfma_f32_16x16x32_bf16 v[8:11], v[64:67], v[8:11], 0
	v_mfma_f32_16x16x32_bf16 v[8:11], v[68:71], v[136:139], v[8:11]
	s_waitcnt lgkmcnt(8)
	v_mfma_f32_16x16x32_bf16 v[12:15], v[64:67], v[12:15], 0
	v_mfma_f32_16x16x32_bf16 v[12:15], v[68:71], v[140:143], v[12:15]
	s_waitcnt lgkmcnt(6)
	v_mfma_f32_16x16x32_bf16 v[16:19], v[64:67], v[16:19], 0
	v_mfma_f32_16x16x32_bf16 v[16:19], v[68:71], v[144:147], v[16:19]
	s_waitcnt lgkmcnt(4)
	v_mfma_f32_16x16x32_bf16 v[20:23], v[64:67], v[20:23], 0
	v_mfma_f32_16x16x32_bf16 v[20:23], v[68:71], v[148:151], v[20:23]
	s_waitcnt lgkmcnt(2)
	v_mfma_f32_16x16x32_bf16 v[24:27], v[64:67], v[24:27], 0
	v_mfma_f32_16x16x32_bf16 v[24:27], v[68:71], v[152:155], v[24:27]
	s_waitcnt lgkmcnt(0)
	v_mfma_f32_16x16x32_bf16 v[28:31], v[64:67], v[28:31], 0
	v_mfma_f32_16x16x32_bf16 v[28:31], v[68:71], v[156:159], v[28:31]
	s_and_saveexec_b64 s[0:1], vcc
	s_xor_b64 s[0:1], exec, s[0:1]
	s_cbranch_execz .LBB0_91
	s_movk_i32 s2, 0x4800
	v_lshlrev_b32_e32 v83, 2, v79
	v_add3_u32 v86, v34, v32, s2
	v_add_u32_e32 v32, v80, v81
	v_lshlrev_b32_e32 v33, 3, v79
	v_sub_u32_e32 v87, v32, v83
	v_mov_b32_e32 v32, 0
	v_mov_b32_e32 v77, v82
	v_add_u32_e32 v84, 1, v45
	v_mad_u32_u24 v85, v81, s4, v33
	s_mov_b64 s[2:3], 0
	v_mov_b32_e32 v88, v83
	v_mov_b32_e32 v33, v32
	v_mov_b32_e32 v34, v32
	v_mov_b32_e32 v35, v32
	v_mov_b32_e32 v36, v32
	v_mov_b32_e32 v37, v32
	v_mov_b32_e32 v38, v32
	v_mov_b32_e32 v39, v32
	v_mov_b32_e32 v56, v32
	v_mov_b32_e32 v57, v32
	v_mov_b32_e32 v58, v32
	v_mov_b32_e32 v59, v32
	v_mov_b32_e32 v60, v32
	v_mov_b32_e32 v61, v32
	v_mov_b32_e32 v62, v32
	v_mov_b32_e32 v63, v32
	v_mov_b32_e32 v40, v32
	v_mov_b32_e32 v41, v32
	v_mov_b32_e32 v42, v32
	v_mov_b32_e32 v43, v32
	v_mov_b32_e32 v48, v32
	v_mov_b32_e32 v49, v32
	v_mov_b32_e32 v50, v32
	v_mov_b32_e32 v51, v32
	v_mov_b32_e32 v44, v32
	v_mov_b32_e32 v45, v32
	v_mov_b32_e32 v46, v32
	v_mov_b32_e32 v47, v32
	v_mov_b32_e32 v52, v32
	v_mov_b32_e32 v53, v32
	v_mov_b32_e32 v54, v32
	v_mov_b32_e32 v55, v32
	s_branch .LBB0_88

; template <int R>
; DEV void sg_core(const bf16_t* __restrict__ A, int lda, const bf16_t* __restrict__ Bt, int ldb, int K, int row0, int col0, f32x4 (&acc)[2], unsigned char* smem) {
;   const int tid = tidx(), lane = tid & 63, wid = tid >> 6, wr = wid >> 1, wc = wid & 1, fr = lane & 15, fq = lane >> 4;
;   const int crow = tid >> 3, ckc = tid & 7;
;   const bf16_t* pa = A + (size_t)(row0 + crow) * lda + ckc * 8;
;   const bf16_t* pb = Bt + (size_t)(col0 + crow) * ldb + ckc * 8;
;   const int nt = K >> 6;
;   const int woff = crow * 144 + ckc * 16;
;   u32x4 ra[R], rb[R];
; #pragma unroll
;   for (int j = 0; j < R; ++j) { ra[j] = *(const u32x4*)(pa + j * 64); rb[j] = *(const u32x4*)(pb + j * 64); }
;   *(u32x4*)(smem + woff) = ra[0]; *(u32x4*)(smem + 9216 + woff) = rb[0];
;   asm volatile("s_waitcnt lgkmcnt(0)\n\ts_barrier" ::: "memory");
;   const int aoff = (wr * 16 + fr) * 144 + fq * 16, boff = 9216 + (wc * 32 + fr) * 144 + fq * 16;
; #pragma unroll 1
;   for (int kt0 = 0; kt0 < nt; kt0 += R) {
; #pragma unroll
;     for (int u = 0; u < R; ++u) {
;       const int kt = kt0 + u;
;       unsigned char* cur = smem + (u & 1) * 18432;
;       unsigned char* nxt = smem + ((u + 1) & 1) * 18432;
;       if (kt + 1 < nt) { *(u32x4*)(nxt + woff) = ra[(u + 1) % R]; *(u32x4*)(nxt + 9216 + woff) = rb[(u + 1) % R]; }
;       if (kt + R < nt) { ra[u] = *(const u32x4*)(pa + (size_t)(kt + R) * 64); rb[u] = *(const u32x4*)(pb + (size_t)(kt + R) * 64); }
; #pragma unroll
;       for (int ks = 0; ks < 2; ++ks) {
;         const bf16x8 af = *(const bf16x8*)(cur + aoff + ks * 64);
; #pragma unroll
;         for (int ni = 0; ni < 2; ++ni) {
;           const bf16x8 bfr = *(const bf16x8*)(cur + boff + ni * 16 * 144 + ks * 64);
;           acc[ni] = mfma32(bfr, af, acc[ni]);
;         }
;       }
;       asm volatile("s_waitcnt lgkmcnt(0)\n\ts_barrier" ::: "memory");
; DEV void sg_branch(const Params& p, unsigned char* smem) {
;     ...
;     for (int s = 0; s < 3; ++s) {
;       const int aoff = (s == 0) ? RG : (s == 1 ? AQ : CB);
;       sg_core<8>(Z + (size_t)TP * NIN + aoff, NIN, W + (size_t)s * D * 512, 512, 512, row0, col0, acc, smem);
;       const int sb = s == 2 ? 2 : s + 1; const float one = s == 2 ? 0.f : 1.f;
;       SG_EPI({
;         const u32x2 ga = *(const u32x2*)(Z + row * NIN + GT + s * D + col), gb = *(const u32x2*)(Z + row * NIN + GT + sb * D + col);
.LBB0_299:
	s_cmp_lg_u32 s4, 0
	s_cbranch_scc1 .Lsgb_pf
	s_cmp_eq_u32 s4, 0x100000
	s_cselect_b32 s6, 0x600, s75
	s_cmp_lg_u32 s4, 0
	s_cselect_b32 s6, s6, 0x400
	s_lshl_b32 s6, s6, 1
	s_add_u32 s12, s15, s6
	v_mov_b32_e32 v74, v171
	s_addc_u32 s13, s16, 0
	v_mov_b64_e32 v[8:9], s[12:13]
	v_ashrrev_i32_e32 v72, 3, v74
	v_add_u32_e32 v10, s35, v72
	v_mad_i64_i32 v[8:9], s[12:13], v10, s95, v[8:9]
	v_lshlrev_b32_e32 v10, 4, v74
	v_and_b32_e32 v168, 0x70, v10
	v_ashrrev_i32_e32 v73, 31, v72
	v_lshl_add_u64 v[64:65], v[8:9], 0, v[168:169]
	v_lshlrev_b64 v[8:9], 10, v[72:73]
	s_add_u32 s12, s21, s4
	v_or_b32_e32 v8, v8, v168
	s_addc_u32 s13, s34, s5
	v_lshl_add_u64 v[12:13], s[12:13], 0, v[8:9]
	global_load_dwordx4 v[8:11], v[64:65], off
	s_mov_b32 s6, 0xd80000
	v_add_co_u32_e32 v68, vcc, s6, v12
	v_mul_lo_u32 v76, v72, s33
	s_nop 0
	v_addc_co_u32_e32 v69, vcc, 0, v13, vcc
	v_mov_b64_e32 v[136:137], v[64:65]
	v_mov_b64_e32 v[138:139], v[68:69]
	global_load_dwordx4 v[12:15], v[68:69], off
	global_load_dwordx4 v[16:19], v[64:65], off offset:128
	global_load_dwordx4 v[20:23], v[68:69], off offset:128
	global_load_dwordx4 v[24:27], v[64:65], off offset:256
	global_load_dwordx4 v[28:31], v[68:69], off offset:256
	global_load_dwordx4 v[32:35], v[64:65], off offset:384
	global_load_dwordx4 v[36:39], v[68:69], off offset:384
	global_load_dwordx4 v[40:43], v[64:65], off offset:512
	global_load_dwordx4 v[44:47], v[68:69], off offset:512
	global_load_dwordx4 v[48:51], v[64:65], off offset:640
	global_load_dwordx4 v[52:55], v[68:69], off offset:640
	global_load_dwordx4 v[56:59], v[64:65], off offset:768
	global_load_dwordx4 v[60:63], v[68:69], off offset:768
	s_nop 0
	global_load_dwordx4 v[64:67], v[64:65], off offset:896
	s_nop 0
	global_load_dwordx4 v[68:71], v[68:69], off offset:896
	s_branch .Lsgb_join
.Lsgb_pf:
	s_waitcnt vmcnt(12)
	v_mov_b32_e32 v74, v171
	v_ashrrev_i32_e32 v72, 3, v74
	v_lshlrev_b32_e32 v10, 4, v74
	v_and_b32_e32 v168, 0x70, v10
	v_mul_lo_u32 v76, v72, s33
	v_mov_b64_e32 v[8:9], v[128:129]
	v_mov_b64_e32 v[10:11], v[130:131]
	v_mov_b64_e32 v[12:13], v[132:133]
	v_mov_b64_e32 v[14:15], v[134:135]
	v_mov_b64_e32 v[16:17], v[140:141]
	v_mov_b64_e32 v[18:19], v[142:143]
	v_mov_b64_e32 v[20:21], v[144:145]
	v_mov_b64_e32 v[22:23], v[146:147]
.Lsgb_join:
	s_movk_i32 s38, 0x600
	s_cmp_eq_u32 s4, 0
	s_cselect_b32 s38, 0x400, s38
	s_mov_b32 s39, 0
	v_lshl_add_u64 v[136:137], v[136:137], 0, s[38:39]
	s_mov_b32 s38, 0x100000
	v_lshl_add_u64 v[138:139], v[138:139], 0, s[38:39]
	v_and_b32_e32 v75, 15, v74
	v_add3_u32 v76, v76, v168, 0
	v_and_b32_e32 v73, 48, v74
	s_cmp_eq_u32 s4, 0x200000
	s_cselect_b64 s[12:13], -1, 0
	v_mov_b32_e32 v119, 0
	v_mov_b32_e32 v109, v171
	v_mov_b32_e32 v114, v171
	v_mov_b32_e32 v113, s27
	v_ashrrev_i32_e32 v110, 3, v114
	v_and_b32_e32 v110, -16, v110
	v_and_b32_e32 v118, 15, v109
	v_ashrrev_i32_e32 v111, 31, v110
	v_or_b32_e32 v112, s26, v118
	v_lshrrev_b32_e32 v114, 1, v114
	v_lshl_add_u64 v[112:113], v[112:113], 0, v[110:111]
	v_and_b32_e32 v116, 32, v114
	v_lshrrev_b32_e32 v109, 2, v109
	v_mov_b64_e32 v[114:115], s[28:29]
	v_and_b32_e32 v109, 12, v109
	v_mad_u64_u32 v[114:115], s[38:39], v112, s95, v[114:115]
	s_and_b64 s[12:13], s[12:13], exec
	v_lshl_add_u64 v[110:111], s[2:3], 0, v[110:111]
	v_add_u32_e32 v112, s20, v116
	v_or3_b32 v117, v109, v116, s19
	v_mad_i32_i24 v115, v113, s95, v115
	s_cselect_b32 s6, 0x800, s36
	v_lshl_add_u64 v[110:111], v[110:111], 0, v[118:119]
	v_add_lshl_u32 v118, v112, v109, 1
	v_lshl_add_u64 v[114:115], s[6:7], 1, v[114:115]
	v_mad_u64_u32 v[112:113], s[38:39], v110, s95, v[118:119]
	v_lshlrev_b32_e32 v118, 1, v117
	v_lshl_add_u64 v[114:115], v[114:115], 0, v[118:119]
	s_mov_b64 s[38:39], 0x4701e00
	s_mov_b32 s6, 0x4701000
	v_lshl_add_u64 v[116:117], v[114:115], 0, s[38:39]
	v_add_co_u32_e32 v114, vcc, s6, v114
	v_mad_i32_i24 v113, v111, s95, v113
	s_nop 0
	v_addc_co_u32_e32 v115, vcc, 0, v115, vcc
	global_load_dwordx2 v[120:121], v[114:115], off offset:3584
	v_lshl_add_u64 v[110:111], s[8:9], 0, v[112:113]
	global_load_dwordx2 v[122:123], v[110:111], off
	global_load_dwordx2 v[124:125], v[110:111], off offset:32
	global_load_dwordx2 v[126:127], v[116:117], off offset:32
	s_waitcnt vmcnt(4)
	ds_write_b128 v76, v[8:11]
	ds_write_b128 v76, v[12:15] offset:9216
	v_and_or_b32 v8, v72, s40, v75
	v_lshrrev_b32_e32 v9, 1, v74
	v_mul_lo_u32 v8, v8, s33
	v_and_or_b32 v9, v9, 32, v75
	s_waitcnt lgkmcnt(0)
	s_barrier
	s_and_b64 vcc, exec, s[12:13]
	s_cbranch_vccnz .Lsgb_np0
	global_load_dwordx4 v[128:131], v[136:137], off
	global_load_dwordx4 v[132:135], v[138:139], off
.Lsgb_np0:
	v_mul_u32_u24_e32 v9, 0x90, v9
	v_add3_u32 v72, 0, v8, v73
	ds_write_b128 v76, v[16:19] offset:18432
	ds_write_b128 v76, v[20:23] offset:27648
	v_add3_u32 v73, 0, v9, v73
	ds_read_b128 v[8:11], v72
	ds_read_b128 v[12:15], v73 offset:9216
	ds_read_b128 v[80:83], v73 offset:11520
	ds_read_b128 v[84:87], v72 offset:64
	ds_read_b128 v[88:91], v73 offset:9280
	ds_read_b128 v[92:95], v73 offset:11584
	s_waitcnt lgkmcnt(4)
	v_mfma_f32_16x16x32_bf16 v[4:7], v[12:15], v[8:11], v[4:7]
	s_waitcnt lgkmcnt(3)
	v_mfma_f32_16x16x32_bf16 v[0:3], v[80:83], v[8:11], v[0:3]
	s_waitcnt lgkmcnt(1)
	v_mfma_f32_16x16x32_bf16 v[4:7], v[88:91], v[84:87], v[4:7]
	s_waitcnt lgkmcnt(0)
	v_mfma_f32_16x16x32_bf16 v[0:3], v[92:95], v[84:87], v[0:3]
	s_waitcnt lgkmcnt(0)
	s_barrier
	s_and_b64 vcc, exec, s[12:13]
	s_cbranch_vccnz .Lsgb_np1
	global_load_dwordx4 v[140:143], v[136:137], off offset:128
	global_load_dwordx4 v[144:147], v[138:139], off offset:128
; DEV f32x4 mfma32(bf16x8 a, bf16x8 b, f32x4 c) { return __builtin_amdgcn_mfma_f32_16x16x32_bf16(a, b, c, 0, 0, 0); }
; template <int R>
; DEV void sg_core(const bf16_t* __restrict__ A, int lda, const bf16_t* __restrict__ Bt, int ldb, int K, int row0, int col0, f32x4 (&acc)[2], unsigned char* smem) {
;     ...
;   for (int kt0 = 0; kt0 < nt; kt0 += R) {
; #pragma unroll
;     for (int u = 0; u < R; ++u) {
;       const int kt = kt0 + u;
;       unsigned char* cur = smem + (u & 1) * 18432;
;       unsigned char* nxt = smem + ((u + 1) & 1) * 18432;
;       if (kt + 1 < nt) { *(u32x4*)(nxt + woff) = ra[(u + 1) % R]; *(u32x4*)(nxt + 9216 + woff) = rb[(u + 1) % R]; }
;       if (kt + R < nt) { ra[u] = *(const u32x4*)(pa + (size_t)(kt + R) * 64); rb[u] = *(const u32x4*)(pb + (size_t)(kt + R) * 64); }
; #pragma unroll
;       for (int ks = 0; ks < 2; ++ks) {
;         const bf16x8 af = *(const bf16x8*)(cur + aoff + ks * 64);
; #pragma unroll
;         for (int ni = 0; ni < 2; ++ni) {
;           const bf16x8 bfr = *(const bf16x8*)(cur + boff + ni * 16 * 144 + ks * 64);
;           acc[ni] = mfma32(bfr, af, acc[ni]);
;         }
;       }
;       asm volatile("s_waitcnt lgkmcnt(0)\n\ts_barrier" ::: "memory");
;     }
.Lsgb_np1:
	ds_write_b128 v76, v[24:27]
	ds_write_b128 v76, v[28:31] offset:9216
	ds_read_b128 v[8:11], v72 offset:18432
	ds_read_b128 v[12:15], v73 offset:27648
	ds_read_b128 v[80:83], v73 offset:29952
	ds_read_b128 v[84:87], v72 offset:18496
	ds_read_b128 v[88:91], v73 offset:27712
	ds_read_b128 v[92:95], v73 offset:30016
	s_waitcnt lgkmcnt(4)
	v_mfma_f32_16x16x32_bf16 v[4:7], v[12:15], v[8:11], v[4:7]
	s_waitcnt lgkmcnt(3)
	v_mfma_f32_16x16x32_bf16 v[0:3], v[80:83], v[8:11], v[0:3]
	s_waitcnt lgkmcnt(1)
	v_mfma_f32_16x16x32_bf16 v[4:7], v[88:91], v[84:87], v[4:7]
	s_waitcnt lgkmcnt(0)
	v_mfma_f32_16x16x32_bf16 v[0:3], v[92:95], v[84:87], v[0:3]
	s_waitcnt lgkmcnt(0)
	s_barrier
	s_and_b64 vcc, exec, s[12:13]
	s_cbranch_vccnz .Lsgb_np2
	global_load_dwordx4 v[24:27], v[136:137], off offset:256
	global_load_dwordx4 v[28:31], v[138:139], off offset:256
.Lsgb_np2:
	ds_write_b128 v76, v[32:35] offset:18432
	ds_write_b128 v76, v[36:39] offset:27648
	ds_read_b128 v[8:11], v72
	ds_read_b128 v[12:15], v73 offset:9216
	ds_read_b128 v[80:83], v73 offset:11520
	ds_read_b128 v[84:87], v72 offset:64
	ds_read_b128 v[88:91], v73 offset:9280
	ds_read_b128 v[92:95], v73 offset:11584
	s_waitcnt lgkmcnt(4)
	v_mfma_f32_16x16x32_bf16 v[4:7], v[12:15], v[8:11], v[4:7]
	s_waitcnt lgkmcnt(3)
	v_mfma_f32_16x16x32_bf16 v[0:3], v[80:83], v[8:11], v[0:3]
	s_waitcnt lgkmcnt(1)
	v_mfma_f32_16x16x32_bf16 v[4:7], v[88:91], v[84:87], v[4:7]
	s_waitcnt lgkmcnt(0)
	v_mfma_f32_16x16x32_bf16 v[0:3], v[92:95], v[84:87], v[0:3]
	s_waitcnt lgkmcnt(0)
	s_barrier
	s_and_b64 vcc, exec, s[12:13]
	s_cbranch_vccnz .Lsgb_np3
	global_load_dwordx4 v[32:35], v[136:137], off offset:384
	global_load_dwordx4 v[36:39], v[138:139], off offset:384
.Lsgb_np3:
	ds_write_b128 v76, v[40:43]
	ds_write_b128 v76, v[44:47] offset:9216
	ds_read_b128 v[8:11], v72 offset:18432
	ds_read_b128 v[12:15], v73 offset:27648
	ds_read_b128 v[80:83], v73 offset:29952
	ds_read_b128 v[84:87], v72 offset:18496
	ds_read_b128 v[88:91], v73 offset:27712
	ds_read_b128 v[92:95], v73 offset:30016
	s_waitcnt lgkmcnt(4)
	v_mfma_f32_16x16x32_bf16 v[4:7], v[12:15], v[8:11], v[4:7]
	s_waitcnt lgkmcnt(3)
	v_mfma_f32_16x16x32_bf16 v[0:3], v[80:83], v[8:11], v[0:3]
	s_waitcnt lgkmcnt(1)
	v_mfma_f32_16x16x32_bf16 v[4:7], v[88:91], v[84:87], v[4:7]
	s_waitcnt lgkmcnt(0)
	v_mfma_f32_16x16x32_bf16 v[0:3], v[92:95], v[84:87], v[0:3]
	s_waitcnt lgkmcnt(0)
	s_barrier
	s_and_b64 vcc, exec, s[12:13]
	s_cbranch_vccnz .Lsgb_np4
	global_load_dwordx4 v[40:43], v[136:137], off offset:512
	global_load_dwordx4 v[44:47], v[138:139], off offset:512
.Lsgb_np4:
	ds_write_b128 v76, v[48:51] offset:18432
	ds_write_b128 v76, v[52:55] offset:27648
	ds_read_b128 v[8:11], v72
	ds_read_b128 v[12:15], v73 offset:9216
	ds_read_b128 v[80:83], v73 offset:11520
	ds_read_b128 v[84:87], v72 offset:64
	ds_read_b128 v[88:91], v73 offset:9280
	ds_read_b128 v[92:95], v73 offset:11584
	s_waitcnt lgkmcnt(4)
	v_mfma_f32_16x16x32_bf16 v[4:7], v[12:15], v[8:11], v[4:7]
	s_waitcnt lgkmcnt(3)
	v_mfma_f32_16x16x32_bf16 v[0:3], v[80:83], v[8:11], v[0:3]
	s_waitcnt lgkmcnt(1)
	v_mfma_f32_16x16x32_bf16 v[4:7], v[88:91], v[84:87], v[4:7]
	s_waitcnt lgkmcnt(0)
	v_mfma_f32_16x16x32_bf16 v[0:3], v[92:95], v[84:87], v[0:3]
	s_waitcnt lgkmcnt(0)
	s_barrier
	s_and_b64 vcc, exec, s[12:13]
	s_cbranch_vccnz .Lsgb_np5
	global_load_dwordx4 v[48:51], v[136:137], off offset:640
	global_load_dwordx4 v[52:55], v[138:139], off offset:640
.Lsgb_np5:
	ds_write_b128 v76, v[56:59]
	ds_write_b128 v76, v[60:63] offset:9216
	ds_read_b128 v[8:11], v72 offset:18432
	ds_read_b128 v[12:15], v73 offset:27648
	ds_read_b128 v[80:83], v73 offset:29952
	ds_read_b128 v[84:87], v72 offset:18496
	ds_read_b128 v[88:91], v73 offset:27712
	ds_read_b128 v[92:95], v73 offset:30016
	s_waitcnt lgkmcnt(4)
	v_mfma_f32_16x16x32_bf16 v[4:7], v[12:15], v[8:11], v[4:7]
	s_waitcnt lgkmcnt(3)
	v_mfma_f32_16x16x32_bf16 v[0:3], v[80:83], v[8:11], v[0:3]
	s_waitcnt lgkmcnt(1)
	v_mfma_f32_16x16x32_bf16 v[4:7], v[88:91], v[84:87], v[4:7]
	s_waitcnt lgkmcnt(0)
	v_mfma_f32_16x16x32_bf16 v[0:3], v[92:95], v[84:87], v[0:3]
	s_waitcnt lgkmcnt(0)
	s_barrier
	s_and_b64 vcc, exec, s[12:13]
	s_cbranch_vccnz .Lsgb_np6
	global_load_dwordx4 v[56:59], v[136:137], off offset:768
	global_load_dwordx4 v[60:63], v[138:139], off offset:768
.Lsgb_np6:
	ds_write_b128 v76, v[64:67] offset:18432
	ds_write_b128 v76, v[68:71] offset:27648
	ds_read_b128 v[8:11], v72
	ds_read_b128 v[12:15], v73 offset:9216
	ds_read_b128 v[80:83], v73 offset:11520
	ds_read_b128 v[84:87], v72 offset:64
	ds_read_b128 v[88:91], v73 offset:9280
	ds_read_b128 v[92:95], v73 offset:11584
	s_waitcnt lgkmcnt(4)
	v_mfma_f32_16x16x32_bf16 v[4:7], v[12:15], v[8:11], v[4:7]
	s_waitcnt lgkmcnt(3)
	v_mfma_f32_16x16x32_bf16 v[0:3], v[80:83], v[8:11], v[0:3]
	s_waitcnt lgkmcnt(1)
	v_mfma_f32_16x16x32_bf16 v[4:7], v[88:91], v[84:87], v[4:7]
	s_waitcnt lgkmcnt(0)
	v_mfma_f32_16x16x32_bf16 v[0:3], v[92:95], v[84:87], v[0:3]
	s_waitcnt lgkmcnt(0)
	s_barrier
	s_and_b64 vcc, exec, s[12:13]
	s_cbranch_vccnz .Lsgb_np7
	global_load_dwordx4 v[64:67], v[136:137], off offset:896
	global_load_dwordx4 v[68:71], v[138:139], off offset:896
.Lsgb_np7:
	ds_read_b128 v[8:11], v72 offset:18432
	ds_read_b128 v[12:15], v73 offset:27648
	ds_read_b128 v[80:83], v73 offset:29952
	ds_read_b128 v[84:87], v72 offset:18496
	ds_read_b128 v[88:91], v73 offset:27712
	ds_read_b128 v[92:95], v73 offset:30016
	s_waitcnt lgkmcnt(4)
	v_mfma_f32_16x16x32_bf16 v[4:7], v[12:15], v[8:11], v[4:7]
	s_waitcnt lgkmcnt(3)
	v_mfma_f32_16x16x32_bf16 v[0:3], v[80:83], v[8:11], v[0:3]
	s_waitcnt lgkmcnt(1)
	v_mfma_f32_16x16x32_bf16 v[4:7], v[88:91], v[84:87], v[4:7]
	s_waitcnt lgkmcnt(0)
	v_mfma_f32_16x16x32_bf16 v[0:3], v[92:95], v[84:87], v[0:3]
	s_waitcnt lgkmcnt(0)
	s_barrier
	s_and_b64 vcc, exec, s[12:13]
	s_cbranch_vccnz .Lsgb_wl
	s_waitcnt vmcnt(16)
	s_branch .Lsgb_wd

; DEV unsigned cvt_pk_bf16(float lo, float hi) { const f32x2_ v = {lo, hi}; return __builtin_bit_cast(unsigned, __builtin_convertvector(v, bf16x2n_)); }
; DEV float bflo(unsigned w) { return __uint_as_float(w << 16); }
; DEV float bfhi(unsigned w) { return __uint_as_float(w & 0xffff0000u); }
; DEV void sg_branch(const Params& p, unsigned char* smem) {
;     ...
;       const int sb = s == 2 ? 2 : s + 1; const float one = s == 2 ? 0.f : 1.f;
;       SG_EPI({
;         const u32x2 ga = *(const u32x2*)(Z + row * NIN + GT + s * D + col), gb = *(const u32x2*)(Z + row * NIN + GT + sb * D + col);
;         acc[ni][0] *= (1.0f + one * __expf(-bflo(gb.x))) * __builtin_amdgcn_rcpf(1.0f + __expf(-bflo(ga.x)));
;         acc[ni][1] *= (1.0f + one * __expf(-bfhi(gb.x))) * __builtin_amdgcn_rcpf(1.0f + __expf(-bfhi(ga.x)));
;         acc[ni][2] *= (1.0f + one * __expf(-bflo(gb.y))) * __builtin_amdgcn_rcpf(1.0f + __expf(-bflo(ga.y)));
;         acc[ni][3] *= (1.0f + one * __expf(-bfhi(gb.y))) * __builtin_amdgcn_rcpf(1.0f + __expf(-bfhi(ga.y)));
;       })
;     }
;     SG_EPI({ u32x2 w; w.x = cvt_pk_bf16(acc[ni][0], acc[ni][1]); w.y = cvt_pk_bf16(acc[ni][2], acc[ni][3]); *(u32x2*)(H + row * D + col) = w; })
;   }
.Lsgb_wd:
	v_mov_b32_e32 v9, v171
	v_mov_b32_e32 v14, v171
	v_mov_b32_e32 v13, s27
	v_ashrrev_i32_e32 v10, 3, v14
	v_and_b32_e32 v10, -16, v10
	v_and_b32_e32 v168, 15, v9
	v_ashrrev_i32_e32 v11, 31, v10
	v_or_b32_e32 v12, s26, v168
	v_lshrrev_b32_e32 v14, 1, v14
	v_lshl_add_u64 v[12:13], v[12:13], 0, v[10:11]
	v_and_b32_e32 v16, 32, v14
	v_lshrrev_b32_e32 v9, 2, v9
	v_mov_b64_e32 v[14:15], s[28:29]
	v_cndmask_b32_e64 v8, 1.0, 0, s[12:13]
	v_and_b32_e32 v9, 12, v9
	v_mad_u64_u32 v[14:15], s[38:39], v12, s95, v[14:15]
	s_and_b64 s[12:13], s[12:13], exec
	v_lshl_add_u64 v[10:11], s[2:3], 0, v[10:11]
	v_add_u32_e32 v12, s20, v16
	v_or3_b32 v17, v9, v16, s19
	v_mad_i32_i24 v15, v13, s95, v15
	s_cselect_b32 s6, 0x800, s36
	v_lshl_add_u64 v[10:11], v[10:11], 0, v[168:169]
	v_add_lshl_u32 v168, v12, v9, 1
	v_lshl_add_u64 v[14:15], s[6:7], 1, v[14:15]
	v_mad_u64_u32 v[12:13], s[12:13], v10, s95, v[168:169]
	v_lshlrev_b32_e32 v168, 1, v17
	v_lshl_add_u64 v[14:15], v[14:15], 0, v[168:169]
	s_mov_b64 s[12:13], 0x4701e00
	s_mov_b32 s6, 0x4701000
	v_lshl_add_u64 v[16:17], v[14:15], 0, s[12:13]
	v_add_co_u32_e32 v14, vcc, s6, v14
	v_mad_i32_i24 v13, v11, s95, v13
	s_nop 0
	v_addc_co_u32_e32 v15, vcc, 0, v15, vcc
	v_mov_b64_e32 v[14:15], v[120:121]
	v_lshl_add_u64 v[10:11], s[8:9], 0, v[12:13]
	v_mov_b64_e32 v[12:13], v[122:123]
	s_add_u32 s4, s4, 0x100000
	s_addc_u32 s5, s5, 0
	s_add_u32 s8, s8, 0x800
	s_addc_u32 s9, s9, 0
	s_addk_i32 s36, 0x400
	s_cmp_eq_u32 s4, 0x300000
	v_lshlrev_b32_e32 v9, 16, v14
	v_mul_f32_e32 v9, 0xbfb8aa3b, v9
	v_exp_f32_e32 v18, v9
	v_lshlrev_b32_e32 v9, 16, v12
	v_mul_f32_e32 v9, 0xbfb8aa3b, v9
	v_exp_f32_e32 v9, v9
	s_nop 0
	v_add_f32_e32 v9, 1.0, v9
	v_rcp_f32_e32 v20, v9
	v_and_b32_e32 v9, 0xffff0000, v14
	v_mul_f32_e32 v9, 0xbfb8aa3b, v9
	v_exp_f32_e32 v19, v9
	v_and_b32_e32 v9, 0xffff0000, v12
	v_mul_f32_e32 v9, 0xbfb8aa3b, v9
	v_exp_f32_e32 v9, v9
	s_nop 0
	v_add_f32_e32 v9, 1.0, v9
	v_rcp_f32_e32 v21, v9
	v_pk_fma_f32 v[18:19], v[8:9], v[18:19], 1.0 op_sel_hi:[0,1,0]
	v_lshlrev_b32_e32 v9, 16, v15
	v_mul_f32_e32 v9, 0xbfb8aa3b, v9
	v_exp_f32_e32 v14, v9
	v_lshlrev_b32_e32 v9, 16, v13
	v_mul_f32_e32 v9, 0xbfb8aa3b, v9
	v_exp_f32_e32 v9, v9
	v_pk_mul_f32 v[18:19], v[20:21], v[18:19]
	v_add_f32_e32 v9, 1.0, v9
	v_rcp_f32_e32 v12, v9
	v_and_b32_e32 v9, 0xffff0000, v15
	v_mul_f32_e32 v9, 0xbfb8aa3b, v9
	v_exp_f32_e32 v15, v9
	v_and_b32_e32 v9, 0xffff0000, v13
	v_mul_f32_e32 v9, 0xbfb8aa3b, v9
	v_exp_f32_e32 v9, v9
	v_pk_mul_f32 v[4:5], v[4:5], v[18:19]
	v_add_f32_e32 v9, 1.0, v9
	v_rcp_f32_e32 v13, v9
	v_pk_fma_f32 v[14:15], v[8:9], v[14:15], 1.0 op_sel_hi:[0,1,0]
	v_pk_mul_f32 v[12:13], v[12:13], v[14:15]
	s_nop 0
	v_pk_mul_f32 v[6:7], v[6:7], v[12:13]
	v_mov_b64_e32 v[10:11], v[124:125]
	s_nop 0
	v_mov_b64_e32 v[12:13], v[126:127]
	v_lshlrev_b32_e32 v9, 16, v12
	v_mul_f32_e32 v9, 0xbfb8aa3b, v9
	v_exp_f32_e32 v14, v9
	v_lshlrev_b32_e32 v9, 16, v10
	v_mul_f32_e32 v9, 0xbfb8aa3b, v9
	v_exp_f32_e32 v9, v9
	s_nop 0
	v_add_f32_e32 v9, 1.0, v9
	v_rcp_f32_e32 v16, v9
	v_and_b32_e32 v9, 0xffff0000, v12
	v_mul_f32_e32 v9, 0xbfb8aa3b, v9
	v_exp_f32_e32 v15, v9
	v_and_b32_e32 v9, 0xffff0000, v10
	v_mul_f32_e32 v9, 0xbfb8aa3b, v9
	v_exp_f32_e32 v9, v9
	s_nop 0
	v_add_f32_e32 v9, 1.0, v9
	v_rcp_f32_e32 v17, v9
	v_pk_fma_f32 v[14:15], v[8:9], v[14:15], 1.0 op_sel_hi:[0,1,0]
	v_lshlrev_b32_e32 v9, 16, v13
	v_mul_f32_e32 v9, 0xbfb8aa3b, v9
	v_exp_f32_e32 v12, v9
	v_lshlrev_b32_e32 v9, 16, v11
	v_mul_f32_e32 v9, 0xbfb8aa3b, v9
	v_exp_f32_e32 v9, v9
	v_pk_mul_f32 v[14:15], v[16:17], v[14:15]
	v_add_f32_e32 v9, 1.0, v9
	v_rcp_f32_e32 v10, v9
	v_and_b32_e32 v9, 0xffff0000, v13
	v_mul_f32_e32 v9, 0xbfb8aa3b, v9
	v_exp_f32_e32 v13, v9
	v_and_b32_e32 v9, 0xffff0000, v11
	v_mul_f32_e32 v9, 0xbfb8aa3b, v9
	v_exp_f32_e32 v9, v9
	v_pk_mul_f32 v[0:1], v[0:1], v[14:15]
	v_add_f32_e32 v9, 1.0, v9
	v_rcp_f32_e32 v11, v9
	v_pk_fma_f32 v[8:9], v[8:9], v[12:13], 1.0 op_sel_hi:[0,1,0]
	v_pk_mul_f32 v[8:9], v[10:11], v[8:9]
	s_nop 0
	v_pk_mul_f32 v[2:3], v[2:3], v[8:9]
	s_cbranch_scc0 .LBB0_299
	v_mov_b32_e32 v12, v171
	v_mov_b32_e32 v13, v171
	v_mov_b32_e32 v11, s27
	v_ashrrev_i32_e32 v8, 3, v13
	v_and_b32_e32 v8, -16, v8
	v_ashrrev_i32_e32 v9, 31, v8
	v_and_or_b32 v10, v12, 15, s26
	v_lshl_add_u64 v[8:9], v[10:11], 0, v[8:9]
	v_lshrrev_b32_e32 v10, 1, v13
	v_lshrrev_b32_e32 v11, 2, v12
	v_and_b32_e32 v10, 32, v10
	v_and_b32_e32 v11, 12, v11
	v_readlane_b32 s36, v248, 37
	v_readlane_b32 s2, v249, 52
	v_or3_b32 v10, v11, v10, s19
	v_lshlrev_b64 v[8:9], 11, v[8:9]
	v_readlane_b32 s38, v248, 39
	s_add_i32 s17, s17, s2
	v_readlane_b32 s2, v249, 33
	v_lshl_add_u64 v[8:9], s[24:25], 0, v[8:9]
	v_lshlrev_b32_e32 v168, 1, v10
	s_add_i32 s14, s14, s38
	s_add_i32 s18, s18, s2
	v_cvt_pk_bf16_f32 v4, v4, v5
	v_cvt_pk_bf16_f32 v5, v6, v7
	v_lshl_add_u64 v[6:7], v[8:9], 0, v[168:169]
	v_cvt_pk_bf16_f32 v0, v0, v1
	v_cvt_pk_bf16_f32 v1, v2, v3
	s_cmpk_gt_i32 s14, 0xff
	global_store_dwordx2 v[6:7], v[4:5], off
	v_readlane_b32 s37, v248, 38
	v_readlane_b32 s39, v248, 40
	global_store_dwordx2 v[6:7], v[0:1], off offset:32
	s_cbranch_scc0 .LBB0_298

; DEV f32x4 mfma32(bf16x8 a, bf16x8 b, f32x4 c) { return __builtin_amdgcn_mfma_f32_16x16x32_bf16(a, b, c, 0, 0, 0); }
; DEV void attn_sample_item(const Params& p, int l, int item, unsigned char* smem) {
;     ...
;   __syncthreads();
;   {
;     const int qt = w & 1, dt = w >> 1;
;     const int r = qt * 16 + fr, qi = r & 7, hh = kvh * 4 + (r >> 3);
;     bf16x8 qf[2];
; #pragma unroll
;     for (int ks = 0; ks < 2; ++ks) qf[ks] = *(const bf16x8*)(Qs + r * 144 + ks * 64 + fq * 16);
;     f32x4 s[9];
; #pragma unroll
;     for (int t = 0; t < 9; ++t) {
;       s[t] = (f32x4){0.f, 0.f, 0.f, 0.f};
; #pragma unroll
;       for (int ks = 0; ks < 2; ++ks) {
;         const bf16x8 kf = *(const bf16x8*)(Ks + (t * 16 + fr) * 144 + ks * 64 + fq * 16);
;         s[t] = mfma32(kf, qf[ks], s[t]);
;       }
;     }
;     const float slope = exp2f(-(float)(hh + 1));
;     const float sink = p.in[I_SINKS][l * 8 + hh];
;     float mx = sink;
; #pragma unroll
;     for (int t = 0; t < 9; ++t)
; #pragma unroll
;       for (int j = 0; j < 4; ++j) {
;         const int kj = t * 16 + fq * 4 + j;
;         const bool okk = (kj > qi) && (kj <= 128 + qi);
;         const float sc = okk ? s[t][j] * 0.125f - slope * (float)(128 + qi - kj) : -INFINITY;
;         s[t][j] = sc; mx = fmaxf(mx, sc);
;       }
.LBB0_350:
	s_or_b64 exec, exec, s[2:3]
	s_and_saveexec_b64 s[0:1], vcc
	v_add3_u32 v4, 0, v4, v38
	ds_write_b128 v4, v[0:3] offset:40192
	s_or_b64 exec, exec, s[0:1]
	v_lshlrev_b32_e32 v0, 4, v36
	v_and_b32_e32 v38, 15, v47
	v_and_b32_e32 v39, 16, v0
	v_and_b32_e32 v1, 48, v47
	v_or_b32_e32 v0, v39, v38
	v_add_u32_e32 v1, 0, v1
	v_lshrrev_b32_e32 v36, 3, v0
	v_mad_u32_u24 v0, v0, s33, v1
	v_mad_u32_u24 v37, v38, s33, v1
	s_waitcnt lgkmcnt(0)
	s_barrier
	ds_read_b128 v[32:35], v0 offset:40192
	ds_read_b128 v[50:53], v0 offset:40256
	ds_read_b128 v[64:67], v37
	ds_read_b128 v[68:71], v37 offset:64
	ds_read_b128 v[72:75], v37 offset:2304
	ds_read_b128 v[76:79], v37 offset:2368
	ds_read_b128 v[80:83], v37 offset:4608
	ds_read_b128 v[84:87], v37 offset:4672
	ds_read_b128 v[88:91], v37 offset:6912
	ds_read_b128 v[92:95], v37 offset:6976
	ds_read_b128 v[96:99], v37 offset:9216
	ds_read_b128 v[100:103], v37 offset:9280
	ds_read_b128 v[104:107], v37 offset:11520
	ds_read_b128 v[108:111], v37 offset:11584
	ds_read_b128 v[112:115], v37 offset:13824
	ds_read_b128 v[116:119], v37 offset:13888
	ds_read_b128 v[120:123], v37 offset:16128
	ds_read_b128 v[124:127], v37 offset:16192
	ds_read_b128 v[128:131], v37 offset:18432
	ds_read_b128 v[132:135], v37 offset:18496
	s_lshl_b32 s2, s26, 2
	v_or_b32_e32 v36, s2, v36
	v_or_b32_e32 v44, s18, v36
	v_ashrrev_i32_e32 v45, 31, v44
	v_lshl_add_u64 v[44:45], v[44:45], 2, s[82:83]
	global_load_dword v42, v[44:45], off
	v_lshrrev_b32_e32 v40, 4, v49
	v_and_b32_e32 v43, 7, v47
	v_lshlrev_b32_e32 v168, 1, v38
	s_waitcnt lgkmcnt(15)
	v_mfma_f32_16x16x32_bf16 v[28:31], v[64:67], v[32:35], 0
	v_mfma_f32_16x16x32_bf16 v[28:31], v[68:71], v[50:53], v[28:31]
	s_waitcnt lgkmcnt(14)
	v_mfma_f32_16x16x32_bf16 v[24:27], v[72:75], v[32:35], 0
	v_mfma_f32_16x16x32_bf16 v[24:27], v[76:79], v[50:53], v[24:27]
	s_waitcnt lgkmcnt(12)
	v_mfma_f32_16x16x32_bf16 v[20:23], v[80:83], v[32:35], 0
	v_mfma_f32_16x16x32_bf16 v[20:23], v[84:87], v[50:53], v[20:23]
	s_waitcnt lgkmcnt(10)
	v_mfma_f32_16x16x32_bf16 v[16:19], v[88:91], v[32:35], 0
	v_mfma_f32_16x16x32_bf16 v[16:19], v[92:95], v[50:53], v[16:19]
	s_waitcnt lgkmcnt(8)
	v_mfma_f32_16x16x32_bf16 v[12:15], v[96:99], v[32:35], 0
	v_mfma_f32_16x16x32_bf16 v[12:15], v[100:103], v[50:53], v[12:15]
	s_waitcnt lgkmcnt(6)
	v_mfma_f32_16x16x32_bf16 v[8:11], v[104:107], v[32:35], 0
	v_mfma_f32_16x16x32_bf16 v[8:11], v[108:111], v[50:53], v[8:11]
	s_waitcnt lgkmcnt(4)
	v_mfma_f32_16x16x32_bf16 v[4:7], v[112:115], v[32:35], 0
	v_mfma_f32_16x16x32_bf16 v[4:7], v[116:119], v[50:53], v[4:7]
	s_waitcnt lgkmcnt(2)
	v_mfma_f32_16x16x32_bf16 v[0:3], v[120:123], v[32:35], 0
	v_mfma_f32_16x16x32_bf16 v[0:3], v[124:127], v[50:53], v[0:3]
	v_add_u32_e32 v37, 1, v36
	v_cvt_f32_ubyte0_e32 v37, v37
	v_cmp_lt_f32_e32 vcc, s41, v37
	s_waitcnt lgkmcnt(0)
	v_mfma_f32_16x16x32_bf16 v[32:35], v[128:131], v[32:35], 0
	v_mfma_f32_16x16x32_bf16 v[32:35], v[132:135], v[50:53], v[32:35]
	v_cndmask_b32_e32 v41, 0, v203, vcc
	v_sub_f32_e32 v37, v41, v37
	v_exp_f32_e32 v37, v37
	v_cndmask_b32_e32 v41, 0, v207, vcc
	v_or_b32_e32 v51, 0x80, v43
	v_ldexp_f32 v37, v37, v41
	v_lshlrev_b32_e32 v41, 2, v40
	v_sub_u32_e32 v36, v51, v41
	v_cvt_f32_ubyte0_e32 v179, v36
	v_mov_b32_e32 v36, v28
	v_pk_mul_f32 v[44:45], v[36:37], v[178:179]
	v_sub_co_u32_e32 v52, vcc, v43, v41
	v_sub_f32_e32 v28, v44, v45
	s_nop 0
	v_cndmask_b32_e32 v44, v205, v28, vcc
	v_xad_u32 v28, v41, -1, v51
	v_cvt_f32_ubyte0_e32 v179, v28
	v_mov_b32_e32 v36, v29
	v_pk_mul_f32 v[28:29], v[36:37], v[178:179]
	v_cmp_le_u32_e64 s[0:1], v43, v41
	v_sub_f32_e32 v28, v28, v29
	v_mov_b32_e32 v36, v30
	v_cndmask_b32_e64 v45, v205, v28, s[0:1]
	v_or_b32_e32 v28, 2, v41
	v_cmp_gt_u32_e64 s[0:1], v28, v43
	v_sub_u32_e32 v28, v51, v28
	v_cvt_f32_ubyte0_e32 v179, v28
	v_pk_mul_f32 v[28:29], v[36:37], v[178:179]
	v_mov_b32_e32 v36, v31
	v_sub_f32_e32 v28, v28, v29
	v_cndmask_b32_e64 v46, v205, v28, s[0:1]
	v_or_b32_e32 v28, 3, v41
	v_cmp_gt_u32_e64 s[0:1], v28, v43
	v_sub_u32_e32 v28, v51, v28
	v_cvt_f32_ubyte0_e32 v179, v28
	v_pk_mul_f32 v[28:29], v[36:37], v[178:179]
	v_sub_u32_e32 v50, v43, v41
	v_sub_f32_e32 v28, v28, v29
	v_cndmask_b32_e64 v49, v205, v28, s[0:1]
	v_add_u32_e32 v28, 14, v50
	v_cvt_f32_u32_e32 v179, v28
	v_mov_b32_e32 v36, v2
	s_movk_i32 s0, 0x130
	v_pk_mul_f32 v[28:29], v[36:37], v[178:179]
	s_nop 0
	v_sub_f32_e32 v2, v28, v29
	v_add_u32_e32 v28, 13, v50
	v_cvt_f32_u32_e32 v179, v28
	v_mov_b32_e32 v36, v3
	v_pk_mul_f32 v[28:29], v[36:37], v[178:179]
	v_cvt_f32_u32_e32 v179, v52
	v_mov_b32_e32 v36, v32
	v_sub_f32_e32 v3, v28, v29
	v_pk_mul_f32 v[28:29], v[36:37], v[178:179]
	s_nop 0
	v_sub_f32_e32 v28, v28, v29
	v_or_b32_e32 v29, 0x81, v41
	v_cndmask_b32_e32 v28, v28, v205, vcc
	v_sub_co_u32_e32 v29, vcc, v51, v29
	v_cvt_f32_u32_e32 v179, v29
	v_mov_b32_e32 v36, v33
	v_pk_mul_f32 v[30:31], v[36:37], v[178:179]
	s_nop 0
	v_sub_f32_e32 v29, v30, v31
	v_or_b32_e32 v30, 0x82, v41
	v_cndmask_b32_e32 v29, v29, v205, vcc
	v_sub_co_u32_e32 v30, vcc, v51, v30
	v_cvt_f32_u32_e32 v179, v30
	v_mov_b32_e32 v36, v34
	v_pk_mul_f32 v[30:31], v[36:37], v[178:179]
	s_nop 0
	v_sub_f32_e32 v30, v30, v31
	v_or_b32_e32 v31, 0x83, v41
	v_cndmask_b32_e32 v30, v30, v205, vcc
	v_sub_co_u32_e32 v31, vcc, v51, v31
	v_cvt_f32_u32_e32 v179, v31
	v_mov_b32_e32 v36, v35
	v_pk_mul_f32 v[32:33], v[36:37], v[178:179]
	s_nop 0
	v_sub_f32_e32 v31, v32, v33
	s_waitcnt vmcnt(0)
; DEV void attn_sample_item(const Params& p, int l, int item, unsigned char* smem) {
;     ...
; #pragma unroll
;     for (int t = 0; t < 9; ++t)
; #pragma unroll
;       for (int j = 0; j < 4; ++j) {
;         const int kj = t * 16 + fq * 4 + j;
;         const bool okk = (kj > qi) && (kj <= 128 + qi);
;         const float sc = okk ? s[t][j] * 0.125f - slope * (float)(128 + qi - kj) : -INFINITY;
;         s[t][j] = sc; mx = fmaxf(mx, sc);
;       }
;     mx = fmaxf(mx, __shfl_xor(mx, 16)); mx = fmaxf(mx, __shfl_xor(mx, 32));
	v_max3_f32 v32, v42, v44, v45
	v_max3_f32 v34, v32, v46, v49
	v_or_b32_e32 v32, 0x70, v43
	v_sub_u32_e32 v32, v32, v41
	v_cvt_f32_ubyte0_e32 v179, v32
	v_mov_b32_e32 v36, v24
	v_pk_mul_f32 v[32:33], v[36:37], v[178:179]
	v_mov_b32_e32 v36, v25
	v_sub_f32_e32 v24, v32, v33
	v_add_u32_e32 v32, 0x6f, v50
	v_cvt_f32_u32_e32 v179, v32
	v_cndmask_b32_e32 v31, v31, v205, vcc
	v_pk_mul_f32 v[32:33], v[36:37], v[178:179]
	s_nop 0
	v_sub_f32_e32 v25, v32, v33
	v_add_u32_e32 v32, 0x6e, v50
	v_cvt_f32_u32_e32 v179, v32
	v_mov_b32_e32 v36, v26
	v_max3_f32 v34, v34, v24, v25
	v_pk_mul_f32 v[32:33], v[36:37], v[178:179]
	s_nop 0
	v_sub_f32_e32 v26, v32, v33
	v_add_u32_e32 v32, 0x6d, v50
	v_cvt_f32_u32_e32 v179, v32
	v_mov_b32_e32 v36, v27
	v_pk_mul_f32 v[32:33], v[36:37], v[178:179]
	s_nop 0
	v_sub_f32_e32 v27, v32, v33
	v_or_b32_e32 v32, 0x60, v43
	v_sub_u32_e32 v32, v32, v41
	v_cvt_f32_ubyte0_e32 v179, v32
	v_mov_b32_e32 v36, v20
	v_pk_mul_f32 v[32:33], v[36:37], v[178:179]
	v_mov_b32_e32 v36, v21
	v_sub_f32_e32 v20, v32, v33
	v_add_u32_e32 v32, 0x5f, v50
	v_cvt_f32_u32_e32 v179, v32
	v_max3_f32 v34, v34, v26, v27
	v_pk_mul_f32 v[32:33], v[36:37], v[178:179]
	s_nop 0
	v_sub_f32_e32 v21, v32, v33
	v_add_u32_e32 v32, 0x5e, v50
	v_cvt_f32_u32_e32 v179, v32
	v_mov_b32_e32 v36, v22
	v_add_u32_e32 v22, 0x5d, v50
	v_max3_f32 v34, v34, v20, v21
	v_pk_mul_f32 v[32:33], v[36:37], v[178:179]
	v_cvt_f32_u32_e32 v179, v22
	v_mov_b32_e32 v36, v23
	v_sub_f32_e32 v32, v32, v33
	v_pk_mul_f32 v[22:23], v[36:37], v[178:179]
	s_nop 0
	v_sub_f32_e32 v33, v22, v23
	v_or_b32_e32 v22, 0x50, v43
	v_sub_u32_e32 v22, v22, v41
	v_cvt_f32_ubyte0_e32 v179, v22
	v_mov_b32_e32 v36, v16
	v_add_u32_e32 v16, 0x4f, v50
	v_pk_mul_f32 v[22:23], v[36:37], v[178:179]
	v_cvt_f32_u32_e32 v179, v16
	v_mov_b32_e32 v36, v17
	v_sub_f32_e32 v22, v22, v23
	v_max3_f32 v34, v34, v32, v33
	v_pk_mul_f32 v[16:17], v[36:37], v[178:179]
	v_mov_b32_e32 v36, v18
	v_sub_f32_e32 v23, v16, v17
	v_add_u32_e32 v16, 0x4e, v50
	v_cvt_f32_u32_e32 v179, v16
	v_max3_f32 v34, v34, v22, v23
	v_pk_mul_f32 v[16:17], v[36:37], v[178:179]
	s_nop 0
	v_sub_f32_e32 v18, v16, v17
	v_add_u32_e32 v16, 0x4d, v50
	v_cvt_f32_u32_e32 v179, v16
	v_mov_b32_e32 v36, v19
	v_pk_mul_f32 v[16:17], v[36:37], v[178:179]
	s_nop 0
	v_sub_f32_e32 v19, v16, v17
	v_or_b32_e32 v16, 64, v43
	v_sub_u32_e32 v16, v16, v41
	v_cvt_f32_ubyte0_e32 v179, v16
	v_mov_b32_e32 v36, v12
	v_add_u32_e32 v12, 63, v50
	v_pk_mul_f32 v[16:17], v[36:37], v[178:179]
	v_cvt_f32_u32_e32 v179, v12
	v_mov_b32_e32 v36, v13
	v_sub_f32_e32 v16, v16, v17
	v_max3_f32 v34, v34, v18, v19
	v_pk_mul_f32 v[12:13], v[36:37], v[178:179]
	v_mov_b32_e32 v36, v14
	v_sub_f32_e32 v17, v12, v13
	v_add_u32_e32 v12, 62, v50
	v_cvt_f32_u32_e32 v179, v12
	v_max3_f32 v34, v34, v16, v17
	v_pk_mul_f32 v[12:13], v[36:37], v[178:179]
	s_nop 0
	v_sub_f32_e32 v14, v12, v13
	v_add_u32_e32 v12, 61, v50
	v_cvt_f32_u32_e32 v179, v12
	v_mov_b32_e32 v36, v15
	v_pk_mul_f32 v[12:13], v[36:37], v[178:179]
	s_nop 0
	v_sub_f32_e32 v15, v12, v13
	v_or_b32_e32 v12, 48, v43
	v_sub_u32_e32 v12, v12, v41
	v_cvt_f32_ubyte0_e32 v179, v12
	v_mov_b32_e32 v36, v8
	v_add_u32_e32 v8, 47, v50
	v_pk_mul_f32 v[12:13], v[36:37], v[178:179]
	v_cvt_f32_u32_e32 v179, v8
	v_mov_b32_e32 v36, v9
	v_sub_f32_e32 v12, v12, v13
	v_max3_f32 v34, v34, v14, v15
	v_pk_mul_f32 v[8:9], v[36:37], v[178:179]
	v_mov_b32_e32 v36, v10
	v_sub_f32_e32 v13, v8, v9
	v_add_u32_e32 v8, 46, v50
	v_cvt_f32_u32_e32 v179, v8
	v_max3_f32 v34, v34, v12, v13
	v_pk_mul_f32 v[8:9], v[36:37], v[178:179]
	s_nop 0
	v_sub_f32_e32 v10, v8, v9
	v_add_u32_e32 v8, 45, v50
	v_cvt_f32_u32_e32 v179, v8
	v_mov_b32_e32 v36, v11
	v_pk_mul_f32 v[8:9], v[36:37], v[178:179]
	s_nop 0
	v_sub_f32_e32 v11, v8, v9
	v_or_b32_e32 v8, 32, v43
	v_sub_u32_e32 v8, v8, v41
	v_cvt_f32_ubyte0_e32 v179, v8
	v_mov_b32_e32 v36, v4
	v_add_u32_e32 v4, 31, v50
	v_pk_mul_f32 v[8:9], v[36:37], v[178:179]
	v_cvt_f32_u32_e32 v179, v4
	v_mov_b32_e32 v36, v5
	v_sub_f32_e32 v8, v8, v9
	v_max3_f32 v34, v34, v10, v11
	v_pk_mul_f32 v[4:5], v[36:37], v[178:179]
	v_mov_b32_e32 v36, v6
	v_sub_f32_e32 v9, v4, v5
	v_add_u32_e32 v4, 30, v50
	v_cvt_f32_u32_e32 v179, v4
	v_max3_f32 v34, v34, v8, v9
	v_pk_mul_f32 v[4:5], v[36:37], v[178:179]
	s_nop 0
	v_sub_f32_e32 v6, v4, v5
	v_add_u32_e32 v4, 29, v50
	v_cvt_f32_u32_e32 v179, v4
	v_mov_b32_e32 v36, v7
	v_pk_mul_f32 v[4:5], v[36:37], v[178:179]
	s_nop 0
	v_sub_f32_e32 v7, v4, v5
	v_or_b32_e32 v4, 16, v43
	v_sub_u32_e32 v4, v4, v41
	v_cvt_f32_ubyte0_e32 v179, v4
	v_mov_b32_e32 v36, v0
	v_add_u32_e32 v0, 15, v50
	v_pk_mul_f32 v[4:5], v[36:37], v[178:179]
	v_cvt_f32_u32_e32 v179, v0
	v_mov_b32_e32 v36, v1
	v_max3_f32 v34, v34, v6, v7
	v_sub_f32_e32 v5, v4, v5
	v_pk_mul_f32 v[0:1], v[36:37], v[178:179]
	v_and_b32_e32 v4, 64, v202
	v_sub_f32_e32 v0, v0, v1
	v_max3_f32 v1, v34, v5, v0
	v_xor_b32_e32 v34, 16, v202
	v_add_u32_e32 v35, 64, v4
	v_max3_f32 v1, v1, v2, v3
	v_cmp_lt_i32_e32 vcc, v34, v35
	v_max3_f32 v1, v1, v28, v29
	v_max3_f32 v1, v1, v30, v31
	v_cndmask_b32_e32 v34, v202, v34, vcc
	v_lshlrev_b32_e32 v34, 2, v34
	ds_bpermute_b32 v36, v34, v1
	v_or_b32_e32 v4, v4, v41
	s_waitcnt lgkmcnt(0)
	v_max_f32_e32 v36, v36, v36
	v_max_f32_e32 v1, v1, v36
	v_xor_b32_e32 v36, 32, v202
	v_cmp_lt_i32_e32 vcc, v36, v35
	s_nop 1
	v_cndmask_b32_e32 v35, v202, v36, vcc
	v_lshlrev_b32_e32 v35, 2, v35
	ds_bpermute_b32 v36, v35, v1
	s_waitcnt lgkmcnt(0)
; DEV void attn_sample_item(const Params& p, int l, int item, unsigned char* smem) {
;     ...
;     mx = fmaxf(mx, __shfl_xor(mx, 16)); mx = fmaxf(mx, __shfl_xor(mx, 32));
;     float sum = 0.f;
; #pragma unroll
;     for (int t = 0; t < 9; ++t)
; #pragma unroll
;       for (int j = 0; j < 4; ++j) { const float e = __expf(s[t][j] - mx); s[t][j] = e; sum += e; }
;     sum += __shfl_xor(sum, 16); sum += __shfl_xor(sum, 32);
	v_max_f32_e32 v36, v36, v36
	v_max_f32_e32 v1, v1, v36
	v_sub_f32_e32 v36, v44, v1
	v_mul_f32_e32 v36, 0x3fb8aa3b, v36
	v_sub_f32_e32 v43, v45, v1
	v_exp_f32_e32 v36, v36
	v_mul_f32_e32 v43, 0x3fb8aa3b, v43
	v_sub_f32_e32 v44, v46, v1
	v_exp_f32_e32 v43, v43
	v_mul_f32_e32 v44, 0x3fb8aa3b, v44
	v_sub_f32_e32 v45, v49, v1
	v_exp_f32_e32 v44, v44
	v_mul_f32_e32 v45, 0x3fb8aa3b, v45
	v_sub_f32_e32 v24, v24, v1
	v_exp_f32_e32 v45, v45
	v_mul_f32_e32 v24, 0x3fb8aa3b, v24
	v_sub_f32_e32 v25, v25, v1
	v_add_f32_e32 v37, 0, v36
	v_exp_f32_e32 v24, v24
	v_mul_f32_e32 v25, 0x3fb8aa3b, v25
	v_sub_f32_e32 v26, v26, v1
	v_add_f32_e32 v37, v43, v37
	v_exp_f32_e32 v25, v25
	v_mul_f32_e32 v26, 0x3fb8aa3b, v26
	v_sub_f32_e32 v27, v27, v1
	v_add_f32_e32 v37, v44, v37
	v_exp_f32_e32 v26, v26
	v_mul_f32_e32 v27, 0x3fb8aa3b, v27
	v_sub_f32_e32 v20, v20, v1
	v_add_f32_e32 v37, v45, v37
	v_exp_f32_e32 v27, v27
	v_mul_f32_e32 v20, 0x3fb8aa3b, v20
	v_sub_f32_e32 v21, v21, v1
	v_add_f32_e32 v37, v24, v37
	v_exp_f32_e32 v20, v20
	v_mul_f32_e32 v21, 0x3fb8aa3b, v21
	v_sub_f32_e32 v32, v32, v1
	v_add_f32_e32 v37, v25, v37
	v_exp_f32_e32 v21, v21
	v_mul_f32_e32 v32, 0x3fb8aa3b, v32
	v_sub_f32_e32 v33, v33, v1
	v_add_f32_e32 v37, v26, v37
	v_exp_f32_e32 v32, v32
	v_mul_f32_e32 v33, 0x3fb8aa3b, v33
	v_sub_f32_e32 v22, v22, v1
	v_add_f32_e32 v37, v27, v37
	v_exp_f32_e32 v33, v33
	v_mul_f32_e32 v22, 0x3fb8aa3b, v22
	v_sub_f32_e32 v23, v23, v1
	v_add_f32_e32 v37, v20, v37
	v_exp_f32_e32 v22, v22
	v_mul_f32_e32 v23, 0x3fb8aa3b, v23
	v_sub_f32_e32 v18, v18, v1
	v_add_f32_e32 v37, v21, v37
	v_exp_f32_e32 v23, v23
	v_mul_f32_e32 v18, 0x3fb8aa3b, v18
	v_sub_f32_e32 v19, v19, v1
	v_add_f32_e32 v37, v32, v37
	v_exp_f32_e32 v18, v18
	v_mul_f32_e32 v19, 0x3fb8aa3b, v19
	v_sub_f32_e32 v16, v16, v1
	v_add_f32_e32 v37, v33, v37
	v_exp_f32_e32 v19, v19
	v_mul_f32_e32 v16, 0x3fb8aa3b, v16
	v_sub_f32_e32 v17, v17, v1
	v_add_f32_e32 v37, v22, v37
	v_exp_f32_e32 v16, v16
	v_mul_f32_e32 v17, 0x3fb8aa3b, v17
	v_sub_f32_e32 v14, v14, v1
	v_add_f32_e32 v37, v23, v37
	v_exp_f32_e32 v17, v17
	v_mul_f32_e32 v14, 0x3fb8aa3b, v14
	v_sub_f32_e32 v15, v15, v1
	v_add_f32_e32 v37, v18, v37
	v_exp_f32_e32 v14, v14
	v_mul_f32_e32 v15, 0x3fb8aa3b, v15
	v_sub_f32_e32 v12, v12, v1
	v_add_f32_e32 v37, v19, v37
	v_exp_f32_e32 v15, v15
	v_mul_f32_e32 v12, 0x3fb8aa3b, v12
	v_add_f32_e32 v37, v16, v37
	v_exp_f32_e32 v46, v12
	v_add_f32_e32 v37, v17, v37
	v_add_f32_e32 v37, v14, v37
	v_sub_f32_e32 v13, v13, v1
	v_add_f32_e32 v37, v15, v37
	v_mul_f32_e32 v13, 0x3fb8aa3b, v13
	v_sub_f32_e32 v10, v10, v1
	v_add_f32_e32 v12, v46, v37
	v_exp_f32_e32 v37, v13
	v_mul_f32_e32 v10, 0x3fb8aa3b, v10
	v_sub_f32_e32 v11, v11, v1
	v_exp_f32_e32 v49, v10
	v_mul_f32_e32 v11, 0x3fb8aa3b, v11
	v_sub_f32_e32 v8, v8, v1
	v_exp_f32_e32 v11, v11
	v_mul_f32_e32 v8, 0x3fb8aa3b, v8
	v_sub_f32_e32 v9, v9, v1
	v_sub_f32_e32 v2, v2, v1
	v_exp_f32_e32 v50, v8
	v_mul_f32_e32 v9, 0x3fb8aa3b, v9
	v_sub_f32_e32 v6, v6, v1
	v_mul_f32_e32 v2, 0x3fb8aa3b, v2
	v_add_f32_e32 v12, v37, v12
	v_exp_f32_e32 v51, v9
	v_mul_f32_e32 v6, 0x3fb8aa3b, v6
	v_sub_f32_e32 v7, v7, v1
	v_exp_f32_e32 v55, v2
	v_sub_f32_e32 v2, v3, v1
	v_add_f32_e32 v10, v49, v12
	v_exp_f32_e32 v52, v6
	v_mul_f32_e32 v7, 0x3fb8aa3b, v7
	v_sub_f32_e32 v5, v5, v1
	v_mul_f32_e32 v2, 0x3fb8aa3b, v2
	v_add_f32_e32 v10, v11, v10
	v_exp_f32_e32 v53, v7
	v_mul_f32_e32 v5, 0x3fb8aa3b, v5
	v_sub_f32_e32 v0, v0, v1
	v_exp_f32_e32 v56, v2
	v_sub_f32_e32 v2, v28, v1
	v_add_f32_e32 v8, v50, v10
	v_exp_f32_e32 v5, v5
	v_mul_f32_e32 v0, 0x3fb8aa3b, v0
	v_mul_f32_e32 v2, 0x3fb8aa3b, v2
	v_add_f32_e32 v8, v51, v8
	v_exp_f32_e32 v54, v0
	v_exp_f32_e32 v28, v2
	v_sub_f32_e32 v2, v29, v1
	v_add_f32_e32 v6, v52, v8
	v_mul_f32_e32 v2, 0x3fb8aa3b, v2
	v_add_f32_e32 v6, v53, v6
	v_exp_f32_e32 v29, v2
	v_sub_f32_e32 v2, v30, v1
	v_add_f32_e32 v6, v5, v6
	v_mul_f32_e32 v2, 0x3fb8aa3b, v2
	v_add_f32_e32 v0, v54, v6
	v_exp_f32_e32 v30, v2
	v_sub_f32_e32 v2, v31, v1
	v_add_f32_e32 v0, v55, v0
	v_mul_f32_e32 v2, 0x3fb8aa3b, v2
	v_add_f32_e32 v0, v56, v0
	v_exp_f32_e32 v31, v2
	v_add_f32_e32 v0, v28, v0
	v_add_f32_e32 v0, v29, v0
	v_add_f32_e32 v0, v30, v0
	v_add_f32_e32 v0, v31, v0
	ds_bpermute_b32 v2, v34, v0
	v_cvt_pk_bf16_f32 v6, v36, v43
	v_cvt_pk_bf16_f32 v7, v44, v45
	v_cvt_pk_bf16_f32 v12, v20, v21
	v_cvt_pk_bf16_f32 v13, v32, v33
	s_waitcnt lgkmcnt(0)
; DEV bf16_t f2bf(float f) { return (bf16_t)(cvt_pk_bf16(f, 0.f) & 0xffffu); }
; DEV f32x4 mfma16(bf16x4 a, bf16x4 b, f32x4 c) { return __builtin_amdgcn_mfma_f32_16x16x16bf16_1k(a, b, c, 0, 0, 0); }
; DEV void attn_sample_item(const Params& p, int l, int item, unsigned char* smem) {
;     ...
;     const float denom = sum + __expf(sink - mx);
;     f32x4 o = (f32x4){0.f, 0.f, 0.f, 0.f};
; #pragma unroll
;     for (int t = 0; t < 9; ++t) {
;       const bf16x4 pf = pack4(s[t][0], s[t][1], s[t][2], s[t][3]);
;       const bf16x4 vf = *(const bf16x4*)(Vt + (dt * 16 + fr) * 152 + t * 16 + fq * 4);
;       o = mfma16(pf, vf, o);
;     }
; #pragma unroll
;     for (int j = 0; j < 4; ++j) {
;       const int ro = qt * 16 + fq * 4 + j;
;       const float inv = 1.0f / __shfl(denom, fq * 4 + j);
;       Z[(rowbase + (ro & 7)) * NIN + AQ + (kvh * 4 + (ro >> 3)) * 64 + dt * 16 + fr] = f2bf(o[j] * inv);
;     }
	v_add_f32_e32 v34, v0, v2
	v_sub_f32_e32 v0, v42, v1
	v_mul_f32_e32 v0, 0x3fb8aa3b, v0
	v_exp_f32_e32 v42, v0
	v_bfi_b32 v0, -16, v48, v47
	v_mul_lo_u32 v0, v0, s0
	v_lshlrev_b32_e32 v1, 3, v40
	v_add3_u32 v40, 0, v0, v1
	v_add_u32_e32 v36, 0x5000, v40
	ds_read2_b64 v[0:3], v36 offset0:32 offset1:36
	s_waitcnt lgkmcnt(0)
	v_mfma_f32_16x16x16_bf16 v[6:9], v[6:7], v[0:1], 0
	v_cvt_pk_bf16_f32 v0, v24, v25
	v_cvt_pk_bf16_f32 v1, v26, v27
	ds_bpermute_b32 v35, v35, v34
	v_and_b32_e32 v10, -16, v48
	v_mfma_f32_16x16x16_bf16 v[0:3], v[0:1], v[2:3], v[6:9]
	s_nop 2
	ds_read2_b64 v[6:9], v36 offset0:40 offset1:44
	s_waitcnt lgkmcnt(0)
	v_mfma_f32_16x16x16_bf16 v[0:3], v[12:13], v[6:7], v[0:3]
	v_cvt_pk_bf16_f32 v6, v22, v23
	v_cvt_pk_bf16_f32 v7, v18, v19
	v_cvt_pk_bf16_f32 v12, v16, v17
	v_cvt_pk_bf16_f32 v13, v14, v15
	v_mfma_f32_16x16x16_bf16 v[0:3], v[6:7], v[8:9], v[0:3]
	ds_read2_b64 v[6:9], v36 offset0:48 offset1:52
	s_waitcnt lgkmcnt(0)
	v_mfma_f32_16x16x16_bf16 v[0:3], v[12:13], v[6:7], v[0:3]
	v_cvt_pk_bf16_f32 v6, v46, v37
	v_cvt_pk_bf16_f32 v7, v49, v11
	v_cvt_pk_bf16_f32 v12, v50, v51
	v_cvt_pk_bf16_f32 v13, v52, v53
	v_mfma_f32_16x16x16_bf16 v[0:3], v[6:7], v[8:9], v[0:3]
	ds_read2_b64 v[6:9], v36 offset0:56 offset1:60
	v_ashrrev_i32_e32 v11, 31, v10
	s_waitcnt lgkmcnt(0)
	v_mfma_f32_16x16x16_bf16 v[0:3], v[12:13], v[6:7], v[0:3]
	v_cvt_pk_bf16_f32 v6, v5, v54
	v_cvt_pk_bf16_f32 v7, v55, v56
	v_add_f32_e32 v5, v34, v35
	s_nop 0
	v_mfma_f32_16x16x16_bf16 v[0:3], v[6:7], v[8:9], v[0:3]
	v_cvt_pk_bf16_f32 v6, v28, v29
	v_cvt_pk_bf16_f32 v7, v30, v31
	ds_read_b64 v[8:9], v40 offset:20992
	s_waitcnt lgkmcnt(0)
	v_mfma_f32_16x16x16_bf16 v[0:3], v[6:7], v[8:9], v[0:3]
	v_add_f32_e32 v8, v42, v5
	v_lshlrev_b32_e32 v9, 2, v4
	v_rcp_f32_e32 v58, v8
	v_lshl_add_u64 v[6:7], v[10:11], 1, s[30:31]
	v_fma_f32 v59, -v8, v58, 1.0
	v_fmac_f32_e32 v58, v59, v58
	v_or_b32_e32 v5, v39, v41
	v_lshrrev_b32_e32 v5, 3, v5
	ds_bpermute_b32 v60, v9, v58
	ds_bpermute_b32 v61, v9, v58 offset:4
	ds_bpermute_b32 v62, v9, v58 offset:8
	ds_bpermute_b32 v63, v9, v58 offset:12
	v_or_b32_e32 v5, s2, v5
	v_lshl_add_u64 v[6:7], v[6:7], 0, v[168:169]
	v_and_or_b32 v4, v41, 4, s6
	s_movk_i32 s0, 0x1b00
	v_mul_lo_u32 v4, v4, s0
	v_lshl_add_u32 v168, v5, 6, v4
	v_lshl_add_u64 v[4:5], v[168:169], 1, v[6:7]
	v_add_co_u32_e32 v6, vcc, 0x4000, v4
	s_nop 1
	v_addc_co_u32_e32 v7, vcc, 0, v5, vcc
	s_nop 1
	v_add_co_u32_e32 v10, vcc, 0x7000, v4
	s_nop 1
	v_addc_co_u32_e32 v11, vcc, 0, v5, vcc
	s_nop 1
	v_add_co_u32_e32 v12, vcc, 0xa000, v4
	s_nop 1
	v_addc_co_u32_e32 v13, vcc, 0, v5, vcc
	s_waitcnt lgkmcnt(0)
	v_mul_f32_e32 v0, v0, v60
	v_mul_f32_e32 v1, v1, v61
	v_mul_f32_e32 v2, v2, v62
	v_mul_f32_e32 v3, v3, v63
	v_cvt_pk_bf16_f32 v0, v0, s0
	v_cvt_pk_bf16_f32 v1, v1, s0
	v_cvt_pk_bf16_f32 v2, v2, s0
	v_cvt_pk_bf16_f32 v3, v3, s0
	global_store_short v[4:5], v0, off offset:3072
	global_store_short v[6:7], v1, off offset:512
	global_store_short v[10:11], v2, off offset:2048
	global_store_short v[12:13], v3, off offset:3584
	s_mov_b64 s[0:1], 0
	s_barrier

; DEV float bflo(unsigned w) { return __uint_as_float(w << 16); }
; DEV float bfhi(unsigned w) { return __uint_as_float(w & 0xffff0000u); }
; DEV void conv_and_window(const Params& p, int l) {
;     ...
;     float u[4][8];
; #pragma unroll
;     for (int k = 0; k < 4; ++k) {
;       if (k >= 2 || t >= 2) {
;         const size_t ro = (size_t)(row - 2 + k) * NIN;
;         const u32x4 a = *(const u32x4*)(Z + ro + CC + c8), hq = *(const u32x4*)(Z + ro + CH + c8);
;         u[k][0] = bflo(a.x) * bflo(hq.x); u[k][1] = bfhi(a.x) * bfhi(hq.x); u[k][2] = bflo(a.y) * bflo(hq.y); u[k][3] = bfhi(a.y) * bfhi(hq.y);
;         u[k][4] = bflo(a.z) * bflo(hq.z); u[k][5] = bfhi(a.z) * bfhi(hq.z); u[k][6] = bflo(a.w) * bflo(hq.w); u[k][7] = bfhi(a.w) * bfhi(hq.w);
;       } else {
; #pragma unroll
;         for (int i = 0; i < 8; ++i) u[k][i] = samp ? p.in[I_SCONV][(size_t)((l * 128 + b) * 2 + k) * 512 + c8 + i] : 0.f;
;       }
;     }
.Lconv_loop:
	v_lshlrev_b32_e32 v108, 16, v68
	v_and_b32_e32 v109, 0xffff0000, v68
	v_lshlrev_b32_e32 v148, 16, v72
	v_and_b32_e32 v149, 0xffff0000, v72
	v_pk_mul_f32 v[108:109], v[108:109], v[148:149]
	v_lshlrev_b32_e32 v110, 16, v69
	v_and_b32_e32 v111, 0xffff0000, v69
	v_lshlrev_b32_e32 v148, 16, v73
	v_and_b32_e32 v149, 0xffff0000, v73
	v_pk_mul_f32 v[110:111], v[110:111], v[148:149]
	v_lshlrev_b32_e32 v112, 16, v70
	v_and_b32_e32 v113, 0xffff0000, v70
	v_lshlrev_b32_e32 v148, 16, v74
	v_and_b32_e32 v149, 0xffff0000, v74
	v_pk_mul_f32 v[112:113], v[112:113], v[148:149]
	v_lshlrev_b32_e32 v114, 16, v71
	v_and_b32_e32 v115, 0xffff0000, v71
	v_lshlrev_b32_e32 v148, 16, v75
	v_and_b32_e32 v149, 0xffff0000, v75
	v_pk_mul_f32 v[114:115], v[114:115], v[148:149]
	v_lshlrev_b32_e32 v116, 16, v76
	v_and_b32_e32 v117, 0xffff0000, v76
	v_lshlrev_b32_e32 v148, 16, v80
	v_and_b32_e32 v149, 0xffff0000, v80
	v_pk_mul_f32 v[116:117], v[116:117], v[148:149]
	v_lshlrev_b32_e32 v118, 16, v77
	v_and_b32_e32 v119, 0xffff0000, v77
	v_lshlrev_b32_e32 v148, 16, v81
	v_and_b32_e32 v149, 0xffff0000, v81
	v_pk_mul_f32 v[118:119], v[118:119], v[148:149]
	v_lshlrev_b32_e32 v120, 16, v78
	v_and_b32_e32 v121, 0xffff0000, v78
	v_lshlrev_b32_e32 v148, 16, v82
	v_and_b32_e32 v149, 0xffff0000, v82
	v_pk_mul_f32 v[120:121], v[120:121], v[148:149]
	v_lshlrev_b32_e32 v122, 16, v79
	v_and_b32_e32 v123, 0xffff0000, v79
	v_lshlrev_b32_e32 v148, 16, v83
	v_and_b32_e32 v149, 0xffff0000, v83
	v_pk_mul_f32 v[122:123], v[122:123], v[148:149]
	v_lshlrev_b32_e32 v124, 16, v84
	v_and_b32_e32 v125, 0xffff0000, v84
	v_lshlrev_b32_e32 v148, 16, v88
	v_and_b32_e32 v149, 0xffff0000, v88
	v_pk_mul_f32 v[124:125], v[124:125], v[148:149]
	v_lshlrev_b32_e32 v126, 16, v85
	v_and_b32_e32 v127, 0xffff0000, v85
	v_lshlrev_b32_e32 v148, 16, v89
	v_and_b32_e32 v149, 0xffff0000, v89
	v_pk_mul_f32 v[126:127], v[126:127], v[148:149]
	v_lshlrev_b32_e32 v128, 16, v86
	v_and_b32_e32 v129, 0xffff0000, v86
	v_lshlrev_b32_e32 v148, 16, v90
	v_and_b32_e32 v149, 0xffff0000, v90
	v_pk_mul_f32 v[128:129], v[128:129], v[148:149]
	v_lshlrev_b32_e32 v130, 16, v87
	v_and_b32_e32 v131, 0xffff0000, v87
	v_lshlrev_b32_e32 v148, 16, v91
	v_and_b32_e32 v149, 0xffff0000, v91
	v_pk_mul_f32 v[130:131], v[130:131], v[148:149]
	v_lshlrev_b32_e32 v132, 16, v92
	v_and_b32_e32 v133, 0xffff0000, v92
	v_lshlrev_b32_e32 v148, 16, v96
	v_and_b32_e32 v149, 0xffff0000, v96
	v_pk_mul_f32 v[132:133], v[132:133], v[148:149]
	v_lshlrev_b32_e32 v134, 16, v93
	v_and_b32_e32 v135, 0xffff0000, v93
	v_lshlrev_b32_e32 v148, 16, v97
	v_and_b32_e32 v149, 0xffff0000, v97
	v_pk_mul_f32 v[134:135], v[134:135], v[148:149]
	v_lshlrev_b32_e32 v136, 16, v94
	v_and_b32_e32 v137, 0xffff0000, v94
	v_lshlrev_b32_e32 v148, 16, v98
	v_and_b32_e32 v149, 0xffff0000, v98
	v_pk_mul_f32 v[136:137], v[136:137], v[148:149]
	v_lshlrev_b32_e32 v138, 16, v95
	v_and_b32_e32 v139, 0xffff0000, v95
	v_lshlrev_b32_e32 v148, 16, v99
	v_and_b32_e32 v149, 0xffff0000, v99
	v_pk_mul_f32 v[138:139], v[138:139], v[148:149]
	v_mov_b64_e32 v[140:141], v[100:101]
	v_mov_b64_e32 v[142:143], v[102:103]
	v_mov_b64_e32 v[144:145], v[104:105]
	v_mov_b64_e32 v[146:147], v[106:107]
	s_mov_b64 s[52:53], s[48:49]
	s_mov_b64 s[54:55], s[50:51]
	s_cmp_ge_u32 s9, 0x4000
	s_cselect_b32 s38, 1, 0
	s_sub_u32 s0, s9, 0x4000
	s_and_b32 s1, s0, 7
	s_lshr_b32 s0, s0, 3
	s_and_b32 s12, s9, 0xfff
	s_lshr_b32 s13, s9, 12
	s_cmp_eq_u32 s38, 1
	s_cselect_b32 s39, s1, s12
	s_cselect_b32 s12, s0, s13
	s_cselect_b32 s13, 6, 0xffe
	s_cmp_lg_u32 s39, 0
	s_cbranch_scc1 .Lconv_nofirst
	s_cmp_eq_u32 s38, 1
	s_cbranch_scc1 .Lconv_state
	v_mov_b64_e32 v[108:109], 0
	v_mov_b64_e32 v[110:111], 0
	v_mov_b64_e32 v[112:113], 0
	v_mov_b64_e32 v[114:115], 0
	v_mov_b64_e32 v[116:117], 0
	v_mov_b64_e32 v[118:119], 0
	v_mov_b64_e32 v[120:121], 0
	v_mov_b64_e32 v[122:123], 0
	s_branch .Lconv_nofirst

; DEV unsigned cvt_pk_bf16(float lo, float hi) { const f32x2_ v = {lo, hi}; return __builtin_bit_cast(unsigned, __builtin_convertvector(v, bf16x2n_)); }
; DEV float bflo(unsigned w) { return __uint_as_float(w << 16); }
; DEV float bfhi(unsigned w) { return __uint_as_float(w & 0xffff0000u); }
; DEV void conv_and_window(const Params& p, int l) {
;     ...
; #pragma unroll
;     for (int k = 0; k < 2; ++k) {
;       const size_t ro = (size_t)(row + k) * NIN;
;       const u32x4 cbv = *(const u32x4*)(Zw + ro + CB + c8);
;       const float cbf[8] = {bflo(cbv.x), bfhi(cbv.x), bflo(cbv.y), bfhi(cbv.y), bflo(cbv.z), bfhi(cbv.z), bflo(cbv.w), bfhi(cbv.w)};
;       float o[8];
; #pragma unroll
;       for (int i = 0; i < 8; ++i) o[i] = cbf[i] * (w0[i] * u[k][i] + w1[i] * u[k + 1][i] + w2[i] * u[k + 2][i]);
;       u32x4 ow; ow.x = cvt_pk_bf16(o[0], o[1]); ow.y = cvt_pk_bf16(o[2], o[3]); ow.z = cvt_pk_bf16(o[4], o[5]); ow.w = cvt_pk_bf16(o[6], o[7]);
;       *(u32x4*)(Zw + ro + CB + c8) = ow;
;     }
;     if (t == T - 2) {
; #pragma unroll
;       for (int k = 0; k < 2; ++k) {
;         float* dst = samp ? p.out + O_CONVS + (size_t)((l * 128 + b) * 2 + k) * 512 + c8
;                           : p.out + O_CONVP + (size_t)((l * 4 + b) * 2 + k) * 512 + c8;
; #pragma unroll
;         for (int i = 0; i < 8; ++i) dst[i] = u[2 + k][i];
;       }
;     }
.Lconv_noload:
	v_pk_mul_f32 v[150:151], v[0:1], v[108:109]
	v_lshlrev_b32_e32 v148, 16, v140
	v_pk_fma_f32 v[150:151], v[8:9], v[116:117], v[150:151]
	v_and_b32_e32 v149, 0xffff0000, v140
	v_pk_fma_f32 v[150:151], v[16:17], v[124:125], v[150:151]
	v_pk_mul_f32 v[150:151], v[148:149], v[150:151]
	v_cvt_pk_bf16_f32 v156, v150, v151
	v_pk_mul_f32 v[152:153], v[2:3], v[110:111]
	v_lshlrev_b32_e32 v154, 16, v141
	v_pk_fma_f32 v[152:153], v[10:11], v[118:119], v[152:153]
	v_and_b32_e32 v155, 0xffff0000, v141
	v_pk_fma_f32 v[152:153], v[18:19], v[126:127], v[152:153]
	v_pk_mul_f32 v[152:153], v[154:155], v[152:153]
	v_cvt_pk_bf16_f32 v157, v152, v153
	v_pk_mul_f32 v[150:151], v[4:5], v[112:113]
	v_lshlrev_b32_e32 v148, 16, v142
	v_pk_fma_f32 v[150:151], v[12:13], v[120:121], v[150:151]
	v_and_b32_e32 v149, 0xffff0000, v142
	v_pk_fma_f32 v[150:151], v[20:21], v[128:129], v[150:151]
	v_pk_mul_f32 v[150:151], v[148:149], v[150:151]
	v_cvt_pk_bf16_f32 v158, v150, v151
	v_pk_mul_f32 v[152:153], v[6:7], v[114:115]
	v_lshlrev_b32_e32 v154, 16, v143
	v_pk_fma_f32 v[152:153], v[14:15], v[122:123], v[152:153]
	v_and_b32_e32 v155, 0xffff0000, v143
	v_pk_fma_f32 v[152:153], v[22:23], v[130:131], v[152:153]
	v_pk_mul_f32 v[152:153], v[154:155], v[152:153]
	v_cvt_pk_bf16_f32 v159, v152, v153
	global_store_dwordx4 v160, v[156:159], s[52:53] offset:-1024
	s_nop 1
	v_pk_mul_f32 v[150:151], v[0:1], v[116:117]
	v_lshlrev_b32_e32 v148, 16, v144
	v_pk_fma_f32 v[150:151], v[8:9], v[124:125], v[150:151]
	v_and_b32_e32 v149, 0xffff0000, v144
	v_pk_fma_f32 v[150:151], v[16:17], v[132:133], v[150:151]
	v_pk_mul_f32 v[150:151], v[148:149], v[150:151]
	v_cvt_pk_bf16_f32 v156, v150, v151
	v_pk_mul_f32 v[152:153], v[2:3], v[118:119]
	v_lshlrev_b32_e32 v154, 16, v145
	v_pk_fma_f32 v[152:153], v[10:11], v[126:127], v[152:153]
	v_and_b32_e32 v155, 0xffff0000, v145
	v_pk_fma_f32 v[152:153], v[18:19], v[134:135], v[152:153]
	v_pk_mul_f32 v[152:153], v[154:155], v[152:153]
	v_cvt_pk_bf16_f32 v157, v152, v153
	v_pk_mul_f32 v[150:151], v[4:5], v[120:121]
	v_lshlrev_b32_e32 v148, 16, v146
	v_pk_fma_f32 v[150:151], v[12:13], v[128:129], v[150:151]
	v_and_b32_e32 v149, 0xffff0000, v146
	v_pk_fma_f32 v[150:151], v[20:21], v[136:137], v[150:151]
	v_pk_mul_f32 v[150:151], v[148:149], v[150:151]
	v_cvt_pk_bf16_f32 v158, v150, v151
	v_pk_mul_f32 v[152:153], v[6:7], v[122:123]
	v_lshlrev_b32_e32 v154, 16, v147
	v_pk_fma_f32 v[152:153], v[14:15], v[130:131], v[152:153]
	v_and_b32_e32 v155, 0xffff0000, v147
	v_pk_fma_f32 v[152:153], v[22:23], v[138:139], v[152:153]
	v_pk_mul_f32 v[152:153], v[154:155], v[152:153]
	v_cvt_pk_bf16_f32 v159, v152, v153
	global_store_dwordx4 v160, v[156:159], s[54:55] offset:-1024
	s_cmp_lg_u32 s39, s13
	s_cbranch_scc1 .Lconv_nolast
	s_cmp_eq_u32 s38, 1
	s_cselect_b32 s0, s17, s18
	s_mov_b32 s1, 0x4600000
	s_mov_b32 s56, 0x8608000
	s_cselect_b32 s1, s56, s1
	s_lshl_b32 s0, s0, 11
	s_lshl_b32 s56, s12, 12
	s_add_u32 s0, s0, s56
	s_add_u32 s0, s0, s1
	s_add_u32 s56, s22, s0
	s_addc_u32 s57, s23, 0
	global_store_dwordx4 v161, v[124:127], s[56:57] offset:0
	global_store_dwordx4 v161, v[128:131], s[56:57] offset:16
	global_store_dwordx4 v161, v[132:135], s[56:57] offset:2048
	global_store_dwordx4 v161, v[136:139], s[56:57] offset:2064
